# barhop+P2-merged-into-P3-with-item-flags
# speedup vs baseline: 1.0226x; 1.0226x over previous
.LBB0_239:
.LBB0_240:
	s_cmp_lt_i32 s72, 3
	s_cselect_b64 s[4:5], -1, 0
	s_add_u32 s48, s70, 0x18c00000
	s_addc_u32 s49, s71, 0
	s_and_b64 s[22:23], s[4:5], s[0:1]
	s_andn2_b64 vcc, exec, s[22:23]
	s_cbranch_vccnz .LBB0_250
	s_cmp_lt_u32 s2, 64
	v_readfirstlane_b32 s3, v143
	s_cbranch_scc1 .LBB0_250
	v_writelane_b32 v240, s2, 0
	v_writelane_b32 v240, s74, 1
	s_mov_b32 s101, s3
	s_sub_u32 s98, s2, 64
	s_and_b32 s99, s98, 63
	s_lshl_b32 s99, s99, 5
	s_lshr_b32 s98, s98, 6
	s_or_b32 s2, s99, s98
	s_add_u32 s100, s99, 32
	s_mov_b32 s74, 3
	s_ashr_i32 s0, s2, 9
	s_ashr_i32 s1, s0, 31
	s_lshl_b32 s4, s2, 6
	v_lshrrev_b32_e32 v56, 7, v143
	s_lshl_b64 s[0:1], s[0:1], 11
	s_and_b32 s4, s4, 0x7c0
	s_or_b32 s0, s0, s4
	s_lshl_b32 s4, s2, 2
	s_waitcnt vmcnt(0)
	v_lshlrev_b32_e32 v22, 4, v56
	v_mov_b32_e32 v23, 0
	v_and_b32_e32 v64, 0x7f, v143
	s_and_b32 s4, s4, 0x780
	v_lshl_add_u64 v[2:3], s[0:1], 0, v[22:23]
	v_or_b32_e32 v58, s4, v64
	v_lshlrev_b64 v[2:3], 11, v[2:3]
	v_readlane_b32 s4, v242, 51
	v_or_b32_e32 v2, v2, v58
	v_readlane_b32 s5, v242, 52
	v_or_b32_e32 v24, 1, v22
	v_mov_b32_e32 v25, v23
	v_lshl_add_u64 v[4:5], v[2:3], 2, s[4:5]
	v_lshlrev_b64 v[2:3], 1, v[2:3]
	v_lshl_add_u64 v[6:7], s[38:39], 0, v[2:3]
	v_lshl_add_u64 v[8:9], s[48:49], 0, v[2:3]
	v_lshl_add_u64 v[2:3], s[0:1], 0, v[24:25]
	v_lshlrev_b64 v[2:3], 11, v[2:3]
	v_or_b32_e32 v2, v2, v58
	v_lshl_add_u64 v[10:11], v[2:3], 2, s[4:5]
	v_lshlrev_b64 v[2:3], 1, v[2:3]
	v_or_b32_e32 v26, 2, v22
	v_mov_b32_e32 v27, v23
	v_lshl_add_u64 v[12:13], s[38:39], 0, v[2:3]
	v_lshl_add_u64 v[14:15], s[48:49], 0, v[2:3]
	v_lshl_add_u64 v[2:3], s[0:1], 0, v[26:27]
	v_lshlrev_b64 v[2:3], 11, v[2:3]
	v_or_b32_e32 v2, v2, v58
	v_lshlrev_b64 v[18:19], 1, v[2:3]
	v_or_b32_e32 v28, 3, v22
	v_mov_b32_e32 v29, v23
	v_or_b32_e32 v30, 4, v22
	v_mov_b32_e32 v31, v23
	v_lshl_add_u64 v[16:17], v[2:3], 2, s[4:5]
	v_lshl_add_u64 v[20:21], s[38:39], 0, v[18:19]
	global_load_dword v2, v[4:5], off
	global_load_ushort v65, v[6:7], off
	global_load_ushort v66, v[8:9], off
	global_load_dword v1, v[10:11], off
	global_load_ushort v67, v[12:13], off
	global_load_ushort v68, v[14:15], off
	global_load_dword v4, v[16:17], off
	global_load_ushort v69, v[20:21], off
	v_lshl_add_u64 v[8:9], s[0:1], 0, v[28:29]
	v_lshl_add_u64 v[12:13], s[0:1], 0, v[30:31]
	v_lshlrev_b64 v[8:9], 11, v[8:9]
	v_lshlrev_b64 v[14:15], 11, v[12:13]
	v_or_b32_e32 v8, v8, v58
	v_or_b32_e32 v14, v14, v58
	v_lshl_add_u64 v[6:7], s[48:49], 0, v[18:19]
	v_lshl_add_u64 v[16:17], v[8:9], 2, s[4:5]
	v_lshlrev_b64 v[8:9], 1, v[8:9]
	v_lshl_add_u64 v[12:13], v[14:15], 2, s[4:5]
	v_lshlrev_b64 v[14:15], 1, v[14:15]
	v_or_b32_e32 v32, 5, v22
	v_mov_b32_e32 v33, v23
	v_or_b32_e32 v36, 7, v22
	v_mov_b32_e32 v37, v23
	v_lshl_add_u64 v[10:11], s[38:39], 0, v[8:9]
	v_lshl_add_u64 v[8:9], s[48:49], 0, v[8:9]
	v_lshl_add_u64 v[18:19], s[38:39], 0, v[14:15]
	v_lshl_add_u64 v[14:15], s[48:49], 0, v[14:15]
	global_load_ushort v77, v[6:7], off
	global_load_ushort v79, v[10:11], off
	global_load_ushort v81, v[8:9], off
	global_load_ushort v82, v[18:19], off
	global_load_ushort v84, v[14:15], off
	v_lshl_add_u64 v[6:7], s[0:1], 0, v[32:33]
	v_or_b32_e32 v34, 6, v22
	v_mov_b32_e32 v35, v23
	v_lshl_add_u64 v[38:39], s[0:1], 0, v[36:37]
	v_lshlrev_b64 v[6:7], 11, v[6:7]
	v_lshl_add_u64 v[10:11], s[0:1], 0, v[34:35]
	v_lshlrev_b64 v[38:39], 11, v[38:39]
	v_or_b32_e32 v6, v6, v58
	v_lshlrev_b64 v[10:11], 11, v[10:11]
	v_or_b32_e32 v38, v38, v58
	v_lshl_add_u64 v[18:19], v[6:7], 2, s[4:5]
	v_lshlrev_b64 v[6:7], 1, v[6:7]
	v_or_b32_e32 v10, v10, v58
	v_lshl_add_u64 v[40:41], v[38:39], 2, s[4:5]
	v_lshlrev_b64 v[38:39], 1, v[38:39]
	v_lshl_add_u64 v[8:9], s[38:39], 0, v[6:7]
	v_lshl_add_u64 v[6:7], s[48:49], 0, v[6:7]
	v_lshl_add_u64 v[14:15], v[10:11], 2, s[4:5]
	v_lshlrev_b64 v[10:11], 1, v[10:11]
	v_lshl_add_u64 v[42:43], s[38:39], 0, v[38:39]
	v_lshl_add_u64 v[38:39], s[48:49], 0, v[38:39]
	v_lshl_add_u64 v[20:21], s[38:39], 0, v[10:11]
	v_lshl_add_u64 v[10:11], s[48:49], 0, v[10:11]
	global_load_ushort v70, v[8:9], off
	global_load_ushort v71, v[6:7], off
	s_nop 0
	global_load_dword v6, v[14:15], off
	global_load_ushort v72, v[20:21], off
	global_load_ushort v73, v[10:11], off
	global_load_dword v7, v[40:41], off
	global_load_ushort v74, v[42:43], off
	global_load_ushort v75, v[38:39], off
	v_or_b32_e32 v38, 8, v22
	v_mov_b32_e32 v39, v23
	v_lshl_add_u64 v[8:9], s[0:1], 0, v[38:39]
	v_lshlrev_b64 v[8:9], 11, v[8:9]
	v_or_b32_e32 v8, v8, v58
	v_lshl_add_u64 v[10:11], v[8:9], 2, s[4:5]
	v_lshlrev_b64 v[8:9], 1, v[8:9]
	v_or_b32_e32 v40, 9, v22
	v_mov_b32_e32 v41, v23
	v_lshl_add_u64 v[14:15], s[38:39], 0, v[8:9]
	v_lshl_add_u64 v[20:21], s[48:49], 0, v[8:9]
	v_lshl_add_u64 v[8:9], s[0:1], 0, v[40:41]
	v_lshlrev_b64 v[8:9], 11, v[8:9]
	v_or_b32_e32 v8, v8, v58
	v_lshl_add_u64 v[44:45], v[8:9], 2, s[4:5]
	v_lshlrev_b64 v[8:9], 1, v[8:9]
	v_or_b32_e32 v42, 10, v22
	v_mov_b32_e32 v43, v23
	v_lshl_add_u64 v[46:47], s[38:39], 0, v[8:9]
	v_lshl_add_u64 v[48:49], s[48:49], 0, v[8:9]
	v_lshl_add_u64 v[8:9], s[0:1], 0, v[42:43]
	v_lshlrev_b64 v[8:9], 11, v[8:9]
	v_or_b32_e32 v8, v8, v58
	v_lshlrev_b64 v[52:53], 1, v[8:9]
	v_lshl_add_u64 v[50:51], v[8:9], 2, s[4:5]
	v_lshl_add_u64 v[54:55], s[38:39], 0, v[52:53]
	global_load_dword v8, v[10:11], off
	global_load_ushort v78, v[14:15], off
	global_load_ushort v80, v[20:21], off
	global_load_dword v9, v[44:45], off
	global_load_ushort v83, v[46:47], off
	global_load_ushort v85, v[48:49], off
	global_load_dword v10, v[50:51], off
	global_load_ushort v86, v[54:55], off
	v_or_b32_e32 v46, 12, v22
	v_mov_b32_e32 v47, v23
	v_or_b32_e32 v44, 11, v22
	v_mov_b32_e32 v45, v23
	v_lshl_add_u64 v[50:51], s[0:1], 0, v[46:47]
	v_lshl_add_u64 v[20:21], s[0:1], 0, v[44:45]
	v_lshlrev_b64 v[50:51], 11, v[50:51]
	v_lshlrev_b64 v[20:21], 11, v[20:21]
	v_or_b32_e32 v50, v50, v58
	v_or_b32_e32 v20, v20, v58
	v_lshl_add_u64 v[108:109], v[50:51], 2, s[4:5]
	v_lshlrev_b64 v[50:51], 1, v[50:51]
	v_lshl_add_u64 v[14:15], s[48:49], 0, v[52:53]
	v_lshl_add_u64 v[62:63], v[20:21], 2, s[4:5]
	v_lshlrev_b64 v[20:21], 1, v[20:21]
	v_lshl_add_u64 v[52:53], s[38:39], 0, v[50:51]
	v_lshl_add_u64 v[50:51], s[48:49], 0, v[50:51]
	v_lshl_add_u64 v[48:49], s[38:39], 0, v[20:21]
	v_lshl_add_u64 v[20:21], s[48:49], 0, v[20:21]
	global_load_ushort v97, v[14:15], off
	global_load_ushort v98, v[48:49], off
	global_load_ushort v99, v[20:21], off
	global_load_ushort v100, v[52:53], off
	global_load_ushort v101, v[50:51], off
	v_or_b32_e32 v50, 14, v22
	v_mov_b32_e32 v51, v23
	v_lshl_add_u64 v[52:53], s[0:1], 0, v[50:51]
	v_lshlrev_b64 v[52:53], 11, v[52:53]
	v_or_b32_e32 v52, v52, v58
	v_lshl_add_u64 v[104:105], v[52:53], 2, s[4:5]
	v_lshlrev_b64 v[52:53], 1, v[52:53]
	v_lshl_add_u64 v[106:107], s[38:39], 0, v[52:53]
	v_lshl_add_u64 v[110:111], s[48:49], 0, v[52:53]
	v_or_b32_e32 v52, 15, v22
	v_mov_b32_e32 v53, v23
	v_or_b32_e32 v48, 13, v22
	v_mov_b32_e32 v49, v23
	v_lshl_add_u64 v[54:55], s[0:1], 0, v[52:53]
	v_lshl_add_u64 v[14:15], s[0:1], 0, v[48:49]
	v_lshlrev_b64 v[54:55], 11, v[54:55]
	v_lshlrev_b64 v[14:15], 11, v[14:15]
	v_or_b32_e32 v54, v54, v58
	v_or_b32_e32 v14, v14, v58
	v_lshl_add_u64 v[112:113], v[54:55], 2, s[4:5]
	v_lshlrev_b64 v[54:55], 1, v[54:55]
	v_and_b32_e32 v5, 0x80, v143
	v_lshl_add_u64 v[20:21], v[14:15], 2, s[4:5]
	v_lshl_add_u64 v[114:115], s[38:39], 0, v[54:55]
	v_lshl_add_u64 v[116:117], s[48:49], 0, v[54:55]
	v_cmp_eq_u32_e64 s[0:1], 0, v5
	v_lshl_add_u32 v5, v64, 1, 0
	s_movk_i32 s4, 0x8e
	v_lshlrev_b32_e32 v54, 1, v143
	v_mad_u32_u24 v11, v64, s4, v5
	v_and_b32_e32 v54, 0x600, v54
	s_add_i32 s4, 0, 0x11800
	v_add_u32_e32 v90, s4, v54
	s_lshr_b32 s4, s3, 3
	v_and_b32_e32 v57, 15, v143
	s_and_b32 s6, s4, 0xffffff0
	s_lshr_b32 s7, s3, 2
	s_and_b32 s5, s4, 0xfffffe0
	v_or_b32_e32 v54, s6, v57
	s_movk_i32 s6, 0x110
	s_and_b32 s7, s7, 16
	v_mul_lo_u32 v54, v54, s6
	s_or_b32 s5, s5, s7
	v_add_u32_e32 v92, 0, v54
	v_or_b32_e32 v54, s5, v57
	v_mul_lo_u32 v54, v54, s6
	v_add_u32_e32 v94, 0, v54
	v_lshrrev_b32_e32 v54, 2, v143
	v_and_b32_e32 v54, 12, v54
	v_and_or_b32 v58, s4, 16, v54
	v_lshlrev_b32_e32 v89, 5, v56
	v_or_b32_e32 v57, s7, v57
	v_mul_u32_u24_e32 v87, 0x1100, v56
	v_or_b32_e32 v56, 2, v58
	v_lshlrev_b32_e32 v54, 3, v143
	v_cmp_gt_u32_e64 s[10:11], v56, v57
	v_or_b32_e32 v56, 3, v58
	v_and_b32_e32 v60, 0x1f8, v54
	v_lshlrev_b32_e32 v54, 4, v143
	v_cmp_gt_u32_e64 s[12:13], v56, v57
	v_lshrrev_b32_e32 v56, 4, v143
	s_lshl_b32 s3, s3, 3
	v_and_b32_e32 v55, 0xf0, v54
	v_mul_u32_u24_e32 v118, 0x110, v56
	v_lshrrev_b32_e32 v56, 3, v143
	s_and_b32 s34, s3, 0xfffffe00
	v_add_u32_e32 v95, 0, v55
	v_and_b32_e32 v55, 0x70, v54
	v_mul_u32_u24_e32 v119, 0x90, v56
	v_add_u32_e32 v56, 0x200, v143
	s_ashr_i32 s3, s2, 31
	v_add_u32_e32 v96, 0, v55
	v_mov_b32_e32 v55, v23
	v_cmp_gt_u32_e64 s[6:7], v58, v57
	v_cmp_lt_u32_e64 s[8:9], v58, v57
	v_lshrrev_b32_e32 v57, 4, v56
	v_lshrrev_b32_e32 v56, 3, v56
	s_lshl_b64 s[24:25], s[2:3], 10
	v_mul_u32_u24_e32 v120, 0x110, v57
	v_mul_u32_u24_e32 v121, 0x90, v56
	v_lshl_add_u64 v[56:57], s[24:25], 0, v[54:55]
	s_mov_b64 s[24:25], 0x17200000
	s_ashr_i32 s29, s74, 31
	s_mov_b32 s28, s74
	s_lshl_b64 s[26:27], s[2:3], 14
	v_lshl_add_u64 v[56:57], v[56:57], 0, s[24:25]
	s_lshl_b64 s[24:25], s[28:29], 10
	v_or_b32_e32 v58, s26, v54
	v_mov_b32_e32 v59, s27
	s_lshl_b64 s[26:27], s[28:29], 14
	s_lshl_b64 s[30:31], s[2:3], 12
	v_lshlrev_b64 v[14:15], 1, v[14:15]
	v_lshlrev_b32_e32 v76, 2, v143
	s_add_u32 s3, s34, s30
	v_lshl_add_u64 v[102:103], s[38:39], 0, v[14:15]
	v_lshl_add_u64 v[14:15], s[48:49], 0, v[14:15]
	v_xor_b32_e32 v3, 0x200, v76
	v_mul_u32_u24_e32 v88, 0x110, v24
	s_addc_u32 s30, 0, s31
	s_add_i32 s41, 0, 0x11c00
	v_add_u32_e32 v55, s41, v3
	v_add_u32_e32 v87, v5, v87
	v_add_u32_e32 v88, v5, v88
	v_add_u32_e32 v89, v11, v89
	global_load_ushort v102, v[102:103], off
	s_nop 0
	global_load_ushort v103, v[14:15], off
	s_nop 0
	global_load_dword v14, v[104:105], off
	s_nop 0
	global_load_ushort v104, v[106:107], off
	global_load_ushort v105, v[110:111], off
	s_nop 0
	global_load_ushort v106, v[114:115], off
	global_load_ushort v107, v[116:117], off
	global_load_dword v15, v[112:113], off
	global_load_dword v5, v[18:19], off
	s_nop 0
	global_load_dword v12, v[12:13], off
	s_nop 0
	global_load_dword v3, v[16:17], off
	global_load_dword v13, v[20:21], off
	s_nop 0
	global_load_dword v16, v[108:109], off
	global_load_dword v11, v[62:63], off
	v_or_b32_e32 v60, s3, v60
	v_mov_b32_e32 v61, s30
	s_mov_b64 s[30:31], 0x16a00000
	v_lshlrev_b32_e32 v91, 2, v64
	v_and_b32_e32 v93, 48, v143
	v_lshl_add_u64 v[60:61], v[60:61], 0, s[30:31]
	s_add_i32 s30, s2, s74
	v_cmp_gt_u32_e64 s[4:5], 64, v143
	s_lshl_b64 s[28:29], s[28:29], 12
	s_lshl_b32 s3, s30, 6
	s_lshl_b32 s36, s74, 6
	s_lshl_b32 s37, s30, 2
	s_lshl_b32 s40, s74, 2
	v_add_u32_e32 v90, v90, v91
	v_add_u32_e32 v91, v92, v93
	v_add_u32_e32 v92, v94, v93
	v_add_u32_e32 v93, v95, v118
	s_brev_b32 s42, 48
	v_add_u32_e32 v94, v96, v119
	s_mov_b32 s43, 0xe000000
	s_brev_b32 s44, 8
	v_add_u32_e32 v95, v95, v120
	v_add_u32_e32 v96, v96, v121
	s_mov_b32 s45, s2
	s_branch .LBB0_244

.LBB0_244:
	s_waitcnt vmcnt(47)
	v_add_f32_e32 v17, 0, v2
	s_waitcnt vmcnt(44)
	v_add_f32_e32 v17, v1, v17
	s_waitcnt vmcnt(41)
	v_add_f32_e32 v17, v4, v17
	s_waitcnt vmcnt(3)
	v_add_f32_e32 v17, v3, v17
	v_add_f32_e32 v17, v12, v17
	v_add_f32_e32 v17, v5, v17
	v_add_f32_e32 v17, v6, v17
	v_add_f32_e32 v17, v7, v17
	v_add_f32_e32 v17, v8, v17
	v_add_f32_e32 v17, v9, v17
	v_add_f32_e32 v17, v10, v17
	s_waitcnt vmcnt(0)
	v_add_f32_e32 v17, v11, v17
	v_add_f32_e32 v17, v16, v17
	v_add_f32_e32 v17, v13, v17
	v_add_f32_e32 v17, v14, v17
	v_add_f32_e32 v18, v15, v17
	v_add_u32_e32 v17, s41, v76
	ds_write_b32 v17, v18
	s_waitcnt lgkmcnt(0)
	s_barrier
	s_cmp_eq_u32 s45, s2
	s_cbranch_scc1 .Lp2_nopub
	s_cmp_gt_u32 s101, 63
	s_cbranch_scc1 .Lp2_nopub
	s_sub_u32 s98, s45, s74
	s_lshl_b32 s98, s98, 2
	s_add_u32 s98, s98, 0x8000
	v_mov_b32_e32 v238, s98
	v_mov_b32_e32 v239, 1
	global_store_dword v238, v239, s[70:71] sc1
.Lp2_nopub:
	ds_read_b32 v20, v55
	v_mov_b32_e32 v21, v1
	s_waitcnt lgkmcnt(0)
	v_cndmask_b32_e64 v17, v20, 0, s[0:1]
	v_add_f32_e32 v19, v2, v17
	v_pk_add_f32 v[62:63], v[20:21], v[18:19]
	v_max_f32_e32 v17, 0xc2a00000, v19
	v_sub_f32_e32 v20, v62, v19
	v_mul_f32_e32 v18, 0x3fb8aa3b, v2
	v_mul_f32_e32 v19, 0x3fb8aa3b, v1
	v_sub_f32_e32 v21, v62, v63
	v_max_f32_e32 v112, 0xc2a00000, v63
	v_exp_f32_e32 v18, v18
	v_exp_f32_e32 v19, v19
	v_mul_f32_e32 v20, 0x3fb8aa3b, v20
	v_mul_f32_e32 v21, 0x3fb8aa3b, v21
	v_mul_f32_e32 v108, 0xbfb8aa3b, v17
	v_mul_f32_e32 v109, 0xbfb8aa3b, v112
	v_exp_f32_e32 v20, v20
	v_exp_f32_e32 v21, v21
	v_exp_f32_e32 v108, v108
	v_exp_f32_e32 v109, v109
	v_add_f32_e32 v63, v4, v63
	v_pk_add_f32 v[18:19], v[18:19], 1.0 op_sel_hi:[1,0] neg_lo:[1,0] neg_hi:[1,0]
	v_add_f32_e32 v110, v3, v63
	v_mul_f32_e32 v113, v18, v108
	v_mul_f32_e32 v114, v19, v109
	v_pk_mul_f32 v[18:19], v[18:19], v[20:21]
	v_mul_f32_e32 v20, 0x3fb8aa3b, v4
	v_mul_f32_e32 v21, 0x3fb8aa3b, v3
	v_sub_f32_e32 v108, v62, v63
	v_sub_f32_e32 v109, v62, v110
	v_max_f32_e32 v63, 0xc2a00000, v63
	v_max_f32_e32 v115, 0xc2a00000, v110
	v_exp_f32_e32 v20, v20
	v_exp_f32_e32 v21, v21
	v_mul_f32_e32 v108, 0x3fb8aa3b, v108
	v_mul_f32_e32 v109, 0x3fb8aa3b, v109
	v_mul_f32_e32 v111, 0xbfb8aa3b, v63
	v_mul_f32_e32 v116, 0xbfb8aa3b, v115
	v_exp_f32_e32 v108, v108
	v_exp_f32_e32 v109, v109
	v_exp_f32_e32 v111, v111
	v_exp_f32_e32 v116, v116
	v_pk_add_f32 v[20:21], v[20:21], 1.0 op_sel_hi:[1,0] neg_lo:[1,0] neg_hi:[1,0]
	v_add_f32_e32 v110, v12, v110
	v_mul_f32_e32 v117, v20, v111
	v_mul_f32_e32 v116, v21, v116
	v_pk_mul_f32 v[20:21], v[20:21], v[108:109]
	v_add_f32_e32 v111, v5, v110
	v_cvt_pk_bf16_f32 v18, v18, v19
	v_cvt_pk_bf16_f32 v19, v20, v21
	v_mul_f32_e32 v20, 0x3fb8aa3b, v12
	v_mul_f32_e32 v21, 0x3fb8aa3b, v5
	v_sub_f32_e32 v108, v62, v110
	v_sub_f32_e32 v109, v62, v111
	v_max_f32_e32 v118, 0xc2a00000, v110
	v_max_f32_e32 v119, 0xc2a00000, v111
	v_exp_f32_e32 v20, v20
	v_exp_f32_e32 v21, v21
	v_mul_f32_e32 v108, 0x3fb8aa3b, v108
	v_mul_f32_e32 v109, 0x3fb8aa3b, v109
	v_mul_f32_e32 v110, 0xbfb8aa3b, v118
	v_mul_f32_e32 v120, 0xbfb8aa3b, v119
	v_exp_f32_e32 v108, v108
	v_exp_f32_e32 v109, v109
	v_exp_f32_e32 v110, v110
	v_exp_f32_e32 v120, v120
	v_pk_add_f32 v[20:21], v[20:21], 1.0 op_sel_hi:[1,0] neg_lo:[1,0] neg_hi:[1,0]
	v_mul_f32_e32 v17, 0x3fb8aa3b, v17
	v_mul_f32_e32 v121, v20, v110
	v_mul_f32_e32 v120, v21, v120
	v_pk_mul_f32 v[20:21], v[20:21], v[108:109]
	v_exp_f32_e32 v17, v17
	v_cvt_pk_bf16_f32 v20, v20, v21
	v_mul_f32_e32 v21, 0x3fb8aa3b, v6
	v_exp_f32_e32 v108, v21
	v_mul_f32_e32 v21, 0x3fb8aa3b, v7
	v_exp_f32_e32 v109, v21
	v_add_f32_e32 v21, v6, v111
	v_add_f32_e32 v122, v7, v21
	v_sub_f32_e32 v110, v62, v21
	v_sub_f32_e32 v111, v62, v122
	v_max_f32_e32 v123, 0xc2a00000, v21
	v_max_f32_e32 v124, 0xc2a00000, v122
	v_mul_f32_e32 v110, 0x3fb8aa3b, v110
	v_mul_f32_e32 v111, 0x3fb8aa3b, v111
	v_mul_f32_e32 v21, 0xbfb8aa3b, v123
	v_mul_f32_e32 v125, 0xbfb8aa3b, v124
	v_exp_f32_e32 v110, v110
	v_exp_f32_e32 v111, v111
	v_exp_f32_e32 v21, v21
	v_exp_f32_e32 v125, v125
	v_pk_add_f32 v[108:109], v[108:109], 1.0 op_sel_hi:[1,0] neg_lo:[1,0] neg_hi:[1,0]
	s_nop 0
	v_mul_f32_e32 v126, v108, v21
	v_mul_f32_e32 v125, v109, v125
	v_pk_mul_f32 v[108:109], v[108:109], v[110:111]
	s_nop 0
	v_cvt_pk_bf16_f32 v21, v108, v109
	v_lshlrev_b32_e32 v108, 16, v65
	v_mul_f32_e32 v17, v17, v108
	v_cvt_pk_bf16_f32 v17, v17, s0
	ds_write_b16 v87, v17
	v_mul_f32_e32 v17, 0x3fb8aa3b, v112
	v_exp_f32_e32 v17, v17
	v_lshlrev_b32_e32 v108, 16, v67
	v_lshlrev_b32_e32 v109, 16, v78
	v_lshlrev_b32_e32 v112, 16, v83
	v_mul_f32_e32 v17, v17, v108
	v_cvt_pk_bf16_f32 v17, v17, s0
	ds_write_b16 v88, v17
	v_cvt_pk_bf16_f32 v17, v113, s0
	ds_write_b16 v87, v17 offset:17408
	v_cvt_pk_bf16_f32 v17, v114, s0
	ds_write_b16 v88, v17 offset:17408
	v_mul_f32_e32 v17, 0x3fb8aa3b, v63
	v_exp_f32_e32 v17, v17
	v_lshlrev_b32_e32 v63, 16, v69
	v_mul_f32_e32 v17, v17, v63
	v_cvt_pk_bf16_f32 v17, v17, s0
	ds_write_b16 v88, v17 offset:272
	v_mul_f32_e32 v17, 0x3fb8aa3b, v115
	v_exp_f32_e32 v17, v17
	v_lshlrev_b32_e32 v63, 16, v79
	v_lshlrev_b32_e32 v115, 16, v98
	v_mul_f32_e32 v17, v17, v63
	v_cvt_pk_bf16_f32 v17, v17, s0
	ds_write_b16 v88, v17 offset:544
	v_cvt_pk_bf16_f32 v17, v117, s0
	ds_write_b16 v88, v17 offset:17680
	v_cvt_pk_bf16_f32 v17, v116, s0
	ds_write_b16 v88, v17 offset:17952
	v_mul_f32_e32 v17, 0x3fb8aa3b, v118
	v_exp_f32_e32 v17, v17
	v_lshlrev_b32_e32 v63, 16, v82
	v_mul_f32_e32 v17, v17, v63
	v_cvt_pk_bf16_f32 v17, v17, s0
	ds_write_b16 v88, v17 offset:816
	v_mul_f32_e32 v17, 0x3fb8aa3b, v119
	v_exp_f32_e32 v17, v17
	v_lshlrev_b32_e32 v63, 16, v70
	v_mul_f32_e32 v17, v17, v63
	v_cvt_pk_bf16_f32 v17, v17, s0
	ds_write_b16 v88, v17 offset:1088
	v_cvt_pk_bf16_f32 v17, v121, s0
	ds_write_b16 v88, v17 offset:18224
	v_cvt_pk_bf16_f32 v17, v120, s0
	ds_write_b16 v88, v17 offset:18496
	v_mul_f32_e32 v17, 0x3fb8aa3b, v123
	v_exp_f32_e32 v17, v17
	v_lshlrev_b32_e32 v63, 16, v72
	v_lshlrev_b32_e32 v121, 16, v102
	v_mul_f32_e32 v17, v17, v63
	v_cvt_pk_bf16_f32 v17, v17, s0
	ds_write_b16 v88, v17 offset:1360
	v_mul_f32_e32 v17, 0x3fb8aa3b, v124
	v_exp_f32_e32 v17, v17
	v_lshlrev_b32_e32 v63, 16, v74
	v_mul_f32_e32 v17, v17, v63
	v_cvt_pk_bf16_f32 v17, v17, s0
	ds_write_b16 v88, v17 offset:1632
	v_cvt_pk_bf16_f32 v17, v126, s0
	ds_write_b16 v88, v17 offset:18768
	v_cvt_pk_bf16_f32 v17, v125, s0
	ds_write_b16 v88, v17 offset:19040
	v_add_f32_e32 v17, v8, v122
	v_max_f32_e32 v63, 0xc2a00000, v17
	v_mul_f32_e32 v108, 0x3fb8aa3b, v63
	v_exp_f32_e32 v108, v108
	v_mul_f32_e32 v63, 0xbfb8aa3b, v63
	v_exp_f32_e32 v63, v63
	v_add_f32_e32 v116, v9, v17
	v_mul_f32_e32 v108, v108, v109
	v_cvt_pk_bf16_f32 v108, v108, s0
	ds_write_b16 v88, v108 offset:1904
	v_mul_f32_e32 v108, 0x3fb8aa3b, v8
	v_mul_f32_e32 v109, 0x3fb8aa3b, v9
	v_exp_f32_e32 v108, v108
	v_exp_f32_e32 v109, v109
	v_max_f32_e32 v110, 0xc2a00000, v116
	v_mul_f32_e32 v111, 0x3fb8aa3b, v110
	v_exp_f32_e32 v111, v111
	v_pk_add_f32 v[108:109], v[108:109], 1.0 op_sel_hi:[1,0] neg_lo:[1,0] neg_hi:[1,0]
	v_lshlrev_b32_e32 v125, 16, v106
	v_mul_f32_e32 v63, v108, v63
	v_cvt_pk_bf16_f32 v63, v63, s0
	ds_write_b16 v88, v63 offset:19312
	v_mul_f32_e32 v63, 0xbfb8aa3b, v110
	v_exp_f32_e32 v63, v63
	v_mul_f32_e32 v111, v111, v112
	v_cvt_pk_bf16_f32 v111, v111, s0
	ds_write_b16 v88, v111 offset:2176
	v_mul_f32_e32 v63, v109, v63
	v_cvt_pk_bf16_f32 v63, v63, s0
	ds_write_b16 v88, v63 offset:19584
	v_add_f32_e32 v63, v10, v116
	v_max_f32_e32 v112, 0xc2a00000, v63
	v_mul_f32_e32 v110, 0x3fb8aa3b, v112
	v_exp_f32_e32 v110, v110
	v_lshlrev_b32_e32 v111, 16, v86
	v_mul_f32_e32 v112, 0xbfb8aa3b, v112
	v_exp_f32_e32 v112, v112
	v_mul_f32_e32 v110, v110, v111
	v_cvt_pk_bf16_f32 v110, v110, s0
	ds_write_b16 v88, v110 offset:2448
	v_mul_f32_e32 v110, 0x3fb8aa3b, v10
	v_mul_f32_e32 v111, 0x3fb8aa3b, v11
	v_exp_f32_e32 v110, v110
	v_exp_f32_e32 v111, v111
	v_add_f32_e32 v117, v11, v63
	v_max_f32_e32 v113, 0xc2a00000, v117
	v_mul_f32_e32 v114, 0x3fb8aa3b, v113
	v_pk_add_f32 v[110:111], v[110:111], 1.0 op_sel_hi:[1,0] neg_lo:[1,0] neg_hi:[1,0]
	v_exp_f32_e32 v114, v114
	v_mul_f32_e32 v112, v110, v112
	v_cvt_pk_bf16_f32 v112, v112, s0
	ds_write_b16 v88, v112 offset:19856
	v_mul_f32_e32 v112, 0xbfb8aa3b, v113
	v_exp_f32_e32 v112, v112
	v_mul_f32_e32 v114, v114, v115
	v_cvt_pk_bf16_f32 v114, v114, s0
	v_add_f32_e32 v118, v16, v117
	v_mul_f32_e32 v112, v111, v112
	ds_write_b16 v88, v114 offset:2720
	v_cvt_pk_bf16_f32 v112, v112, s0
	v_max_f32_e32 v114, 0xc2a00000, v118
	ds_write_b16 v88, v112 offset:20128
	v_mul_f32_e32 v112, 0x3fb8aa3b, v114
	v_exp_f32_e32 v112, v112
	v_lshlrev_b32_e32 v113, 16, v100
	v_mul_f32_e32 v114, 0xbfb8aa3b, v114
	v_exp_f32_e32 v114, v114
	v_mul_f32_e32 v112, v112, v113
	v_cvt_pk_bf16_f32 v112, v112, s0
	ds_write_b16 v88, v112 offset:2992
	v_mul_f32_e32 v112, 0x3fb8aa3b, v16
	v_mul_f32_e32 v113, 0x3fb8aa3b, v13
	v_exp_f32_e32 v112, v112
	v_exp_f32_e32 v113, v113
	v_add_f32_e32 v119, v13, v118
	v_max_f32_e32 v115, 0xc2a00000, v119
	v_mul_f32_e32 v120, 0x3fb8aa3b, v115
	v_pk_add_f32 v[112:113], v[112:113], 1.0 op_sel_hi:[1,0] neg_lo:[1,0] neg_hi:[1,0]
	v_exp_f32_e32 v120, v120
	v_mul_f32_e32 v114, v112, v114
	v_cvt_pk_bf16_f32 v114, v114, s0
	ds_write_b16 v88, v114 offset:20400
	v_mul_f32_e32 v114, 0xbfb8aa3b, v115
	v_exp_f32_e32 v114, v114
	v_mul_f32_e32 v120, v120, v121
	v_cvt_pk_bf16_f32 v120, v120, s0
	ds_write_b16 v88, v120 offset:3264
	v_mul_f32_e32 v114, v113, v114
	v_add_f32_e32 v120, v14, v119
	v_cvt_pk_bf16_f32 v114, v114, s0
	v_max_f32_e32 v121, 0xc2a00000, v120
	ds_write_b16 v88, v114 offset:20672
	v_mul_f32_e32 v114, 0x3fb8aa3b, v121
	v_exp_f32_e32 v114, v114
	v_lshlrev_b32_e32 v115, 16, v104
	v_mul_f32_e32 v121, 0xbfb8aa3b, v121
	v_exp_f32_e32 v121, v121
	v_mul_f32_e32 v114, v114, v115
	v_cvt_pk_bf16_f32 v114, v114, s0
	ds_write_b16 v88, v114 offset:3536
	v_mul_f32_e32 v114, 0x3fb8aa3b, v14
	v_mul_f32_e32 v115, 0x3fb8aa3b, v15
	v_exp_f32_e32 v114, v114
	v_exp_f32_e32 v115, v115
	v_add_f32_e32 v122, v15, v120
	v_max_f32_e32 v123, 0xc2a00000, v122
	v_mul_f32_e32 v124, 0x3fb8aa3b, v123
	v_pk_add_f32 v[114:115], v[114:115], 1.0 op_sel_hi:[1,0] neg_lo:[1,0] neg_hi:[1,0]
	v_exp_f32_e32 v124, v124
	v_mul_f32_e32 v121, v114, v121
	v_cvt_pk_bf16_f32 v121, v121, s0
	ds_write_b16 v88, v121 offset:20944
	v_mul_f32_e32 v121, 0xbfb8aa3b, v123
	v_exp_f32_e32 v121, v121
	v_mul_f32_e32 v124, v124, v125
	v_cvt_pk_bf16_f32 v124, v124, s0
	v_sub_f32_e32 v17, v62, v17
	v_mul_f32_e32 v121, v115, v121
	v_cvt_pk_bf16_f32 v121, v121, s0
	ds_write_b16 v88, v124 offset:3808
	ds_write_b16 v88, v121 offset:21216
	ds_write_b128 v89, v[18:21] offset:34816
	v_mul_f32_e32 v17, 0x3fb8aa3b, v17
	v_sub_f32_e32 v18, v62, v116
	v_mul_f32_e32 v19, 0x3fb8aa3b, v18
	v_exp_f32_e32 v18, v17
	v_sub_f32_e32 v17, v62, v63
	v_sub_f32_e32 v20, v62, v117
	v_mul_f32_e32 v17, 0x3fb8aa3b, v17
	v_mul_f32_e32 v21, 0x3fb8aa3b, v20
	v_exp_f32_e32 v19, v19
	v_exp_f32_e32 v20, v17
	v_exp_f32_e32 v21, v21
	v_sub_f32_e32 v17, v62, v118
	v_pk_mul_f32 v[18:19], v[108:109], v[18:19]
	v_mul_f32_e32 v17, 0x3fb8aa3b, v17
	v_pk_mul_f32 v[20:21], v[110:111], v[20:21]
	v_cvt_pk_bf16_f32 v18, v18, v19
	v_cvt_pk_bf16_f32 v19, v20, v21
	v_sub_f32_e32 v20, v62, v119
	v_mul_f32_e32 v21, 0x3fb8aa3b, v20
	v_exp_f32_e32 v20, v17
	v_exp_f32_e32 v21, v21
	v_sub_f32_e32 v17, v62, v120
	v_mul_f32_e32 v17, 0x3fb8aa3b, v17
	v_exp_f32_e32 v108, v17
	v_pk_mul_f32 v[20:21], v[112:113], v[20:21]
	s_nop 0
	v_cvt_pk_bf16_f32 v20, v20, v21
	v_sub_f32_e32 v21, v62, v122
	v_mul_f32_e32 v21, 0x3fb8aa3b, v21
	v_exp_f32_e32 v109, v21
	s_nop 0
	v_pk_mul_f32 v[108:109], v[114:115], v[108:109]
	s_nop 0
	v_cvt_pk_bf16_f32 v21, v108, v109
	ds_write_b128 v89, v[18:21] offset:34832
	v_lshl_or_b32 v18, v68, 16, v66
	v_lshl_or_b32 v19, v81, 16, v77
	v_lshl_or_b32 v20, v71, 16, v84
	v_lshl_or_b32 v21, v75, 16, v73
	ds_write_b128 v89, v[18:21] offset:53248
	v_lshl_or_b32 v18, v85, 16, v80
	v_lshl_or_b32 v19, v99, 16, v97
	v_lshl_or_b32 v20, v103, 16, v101
	v_lshl_or_b32 v21, v107, 16, v105
	ds_write_b128 v89, v[18:21] offset:53264
	s_and_saveexec_b64 s[30:31], s[0:1]
	s_cbranch_execz .LBB0_246
	v_mul_f32_e32 v17, 0x3fb8aa3b, v62
	v_exp_f32_e32 v17, v17
	ds_write_b32 v90, v17
.LBB0_246:
	s_or_b64 exec, exec, s[30:31]
	s_add_i32 s45, s45, s74
	s_waitcnt lgkmcnt(0)
	s_barrier
	s_cmp_ge_i32 s45, s100
	s_cselect_b64 s[30:31], -1, 0
	s_and_b64 vcc, exec, s[30:31]
	s_cbranch_vccnz .LBB0_248
	s_ashr_i32 s34, s45, 9
	s_ashr_i32 s35, s34, 31
	s_lshl_b64 s[34:35], s[34:35], 11
	s_and_b32 s46, s3, 0x7c0
	s_or_b32 s34, s34, s46
	s_and_b32 s46, s37, 0x780
	v_lshl_add_u64 v[2:3], s[34:35], 0, v[22:23]
	v_or_b32_e32 v77, s46, v64
	v_lshlrev_b64 v[2:3], 11, v[2:3]
	v_readlane_b32 s46, v242, 51
	v_or_b32_e32 v2, v2, v77
	v_readlane_b32 s47, v242, 52
	v_lshl_add_u64 v[70:71], s[34:35], 0, v[36:37]
	v_lshlrev_b64 v[70:71], 11, v[70:71]
	v_lshl_add_u64 v[4:5], v[2:3], 2, s[46:47]
	v_lshlrev_b64 v[2:3], 1, v[2:3]
	v_lshl_add_u64 v[6:7], s[38:39], 0, v[2:3]
	v_lshl_add_u64 v[8:9], s[48:49], 0, v[2:3]
	v_lshl_add_u64 v[2:3], s[34:35], 0, v[24:25]
	v_lshlrev_b64 v[2:3], 11, v[2:3]
	v_or_b32_e32 v2, v2, v77
	v_lshl_add_u64 v[10:11], v[2:3], 2, s[46:47]
	v_lshlrev_b64 v[2:3], 1, v[2:3]
	v_lshl_add_u64 v[12:13], s[38:39], 0, v[2:3]
	v_lshl_add_u64 v[14:15], s[48:49], 0, v[2:3]
	v_lshl_add_u64 v[2:3], s[34:35], 0, v[26:27]
	v_lshlrev_b64 v[2:3], 11, v[2:3]
	v_or_b32_e32 v2, v2, v77
	v_lshlrev_b64 v[18:19], 1, v[2:3]
	v_lshl_add_u64 v[16:17], v[2:3], 2, s[46:47]
	v_lshl_add_u64 v[20:21], s[38:39], 0, v[18:19]
	global_load_dword v2, v[4:5], off
	global_load_ushort v65, v[6:7], off
	global_load_ushort v66, v[8:9], off
	global_load_dword v1, v[10:11], off
	global_load_ushort v67, v[12:13], off
	global_load_ushort v68, v[14:15], off
	global_load_dword v4, v[16:17], off
	global_load_ushort v69, v[20:21], off
	v_lshl_add_u64 v[6:7], s[34:35], 0, v[28:29]
	v_lshlrev_b64 v[6:7], 11, v[6:7]
	v_or_b32_e32 v6, v6, v77
	v_lshl_add_u64 v[16:17], v[6:7], 2, s[46:47]
	v_lshlrev_b64 v[6:7], 1, v[6:7]
	v_lshl_add_u64 v[12:13], s[48:49], 0, v[18:19]
	v_lshl_add_u64 v[18:19], s[38:39], 0, v[6:7]
	v_lshl_add_u64 v[20:21], s[48:49], 0, v[6:7]
	v_lshl_add_u64 v[6:7], s[34:35], 0, v[30:31]
	v_lshlrev_b64 v[6:7], 11, v[6:7]
	v_or_b32_e32 v6, v6, v77
	v_lshl_add_u64 v[62:63], v[6:7], 2, s[46:47]
	v_lshlrev_b64 v[6:7], 1, v[6:7]
	v_lshl_add_u64 v[108:109], s[38:39], 0, v[6:7]
	v_lshl_add_u64 v[110:111], s[48:49], 0, v[6:7]
	v_lshl_add_u64 v[6:7], s[34:35], 0, v[32:33]
	v_lshl_add_u64 v[10:11], s[34:35], 0, v[34:35]
	v_lshlrev_b64 v[6:7], 11, v[6:7]
	v_lshlrev_b64 v[10:11], 11, v[10:11]
	v_or_b32_e32 v6, v6, v77
	v_or_b32_e32 v10, v10, v77
	v_lshl_add_u64 v[112:113], v[6:7], 2, s[46:47]
	v_lshlrev_b64 v[6:7], 1, v[6:7]
	v_lshl_add_u64 v[14:15], v[10:11], 2, s[46:47]
	v_lshlrev_b64 v[10:11], 1, v[10:11]
	v_or_b32_e32 v70, v70, v77
	v_lshl_add_u64 v[8:9], s[38:39], 0, v[6:7]
	v_lshl_add_u64 v[6:7], s[48:49], 0, v[6:7]
	v_lshl_add_u64 v[72:73], s[38:39], 0, v[10:11]
	v_lshl_add_u64 v[74:75], v[70:71], 2, s[46:47]
	v_lshlrev_b64 v[70:71], 1, v[70:71]
	v_lshl_add_u64 v[10:11], s[48:49], 0, v[10:11]
	v_lshl_add_u64 v[78:79], s[38:39], 0, v[70:71]
	v_lshl_add_u64 v[80:81], s[48:49], 0, v[70:71]
	global_load_ushort v70, v[8:9], off
	global_load_ushort v71, v[6:7], off
	s_nop 0
	global_load_dword v6, v[14:15], off
	s_nop 0
	global_load_ushort v72, v[72:73], off
	s_nop 0
	global_load_ushort v73, v[10:11], off
	global_load_dword v7, v[74:75], off
	s_nop 0
	global_load_ushort v74, v[78:79], off
	global_load_ushort v75, v[80:81], off
	v_lshl_add_u64 v[8:9], s[34:35], 0, v[38:39]
	v_lshlrev_b64 v[8:9], 11, v[8:9]
	v_or_b32_e32 v8, v8, v77
	v_lshl_add_u64 v[10:11], v[8:9], 2, s[46:47]
	v_lshlrev_b64 v[8:9], 1, v[8:9]
	v_lshl_add_u64 v[14:15], s[38:39], 0, v[8:9]
	v_lshl_add_u64 v[80:81], s[48:49], 0, v[8:9]
	v_lshl_add_u64 v[8:9], s[34:35], 0, v[40:41]
	v_lshlrev_b64 v[8:9], 11, v[8:9]
	v_or_b32_e32 v8, v8, v77
	v_lshl_add_u64 v[82:83], v[8:9], 2, s[46:47]
	v_lshlrev_b64 v[8:9], 1, v[8:9]
	v_lshl_add_u64 v[84:85], s[38:39], 0, v[8:9]
	v_lshl_add_u64 v[98:99], s[48:49], 0, v[8:9]
	v_lshl_add_u64 v[8:9], s[34:35], 0, v[42:43]
	v_lshlrev_b64 v[8:9], 11, v[8:9]
	v_or_b32_e32 v8, v8, v77
	v_lshlrev_b64 v[102:103], 1, v[8:9]
	v_lshl_add_u64 v[100:101], v[8:9], 2, s[46:47]
	v_lshl_add_u64 v[104:105], s[38:39], 0, v[102:103]
	global_load_dword v8, v[10:11], off
	global_load_ushort v78, v[14:15], off
	s_nop 0
	global_load_ushort v80, v[80:81], off
	s_nop 0
	global_load_dword v9, v[82:83], off
	s_nop 0
	global_load_ushort v83, v[84:85], off
	s_nop 0
	global_load_ushort v85, v[98:99], off
	global_load_dword v10, v[100:101], off
	global_load_ushort v86, v[104:105], off
	v_lshl_add_u64 v[98:99], s[34:35], 0, v[44:45]
	v_lshlrev_b64 v[98:99], 11, v[98:99]
	v_or_b32_e32 v98, v98, v77
	v_lshl_add_u64 v[114:115], v[98:99], 2, s[46:47]
	v_lshlrev_b64 v[98:99], 1, v[98:99]
	v_lshl_add_u64 v[14:15], s[48:49], 0, v[102:103]
	v_lshl_add_u64 v[100:101], s[38:39], 0, v[98:99]
	v_lshl_add_u64 v[102:103], s[48:49], 0, v[98:99]
	v_lshl_add_u64 v[98:99], s[34:35], 0, v[46:47]
	v_lshlrev_b64 v[98:99], 11, v[98:99]
	v_or_b32_e32 v98, v98, v77
	v_lshl_add_u64 v[116:117], v[98:99], 2, s[46:47]
	v_lshlrev_b64 v[98:99], 1, v[98:99]
	v_lshl_add_u64 v[104:105], s[38:39], 0, v[98:99]
	v_lshl_add_u64 v[106:107], s[48:49], 0, v[98:99]
	global_load_ushort v97, v[14:15], off
	global_load_ushort v98, v[100:101], off
	global_load_ushort v99, v[102:103], off
	s_nop 0
	global_load_ushort v100, v[104:105], off
	global_load_ushort v101, v[106:107], off
	v_lshl_add_u64 v[104:105], s[34:35], 0, v[50:51]
	v_lshlrev_b64 v[104:105], 11, v[104:105]
	v_or_b32_e32 v104, v104, v77
	v_lshl_add_u64 v[14:15], s[34:35], 0, v[48:49]
	v_lshl_add_u64 v[106:107], v[104:105], 2, s[46:47]
	v_lshlrev_b64 v[104:105], 1, v[104:105]
	v_lshlrev_b64 v[14:15], 11, v[14:15]
	v_lshl_add_u64 v[120:121], s[38:39], 0, v[104:105]
	v_lshl_add_u64 v[122:123], s[48:49], 0, v[104:105]
	v_lshl_add_u64 v[104:105], s[34:35], 0, v[52:53]
	v_or_b32_e32 v14, v14, v77
	v_lshlrev_b64 v[104:105], 11, v[104:105]
	v_lshl_add_u64 v[118:119], v[14:15], 2, s[46:47]
	v_lshlrev_b64 v[14:15], 1, v[14:15]
	v_or_b32_e32 v104, v104, v77
	v_lshl_add_u64 v[102:103], s[38:39], 0, v[14:15]
	v_lshl_add_u64 v[14:15], s[48:49], 0, v[14:15]
	v_lshl_add_u64 v[124:125], v[104:105], 2, s[46:47]
	v_lshlrev_b64 v[104:105], 1, v[104:105]
	v_lshl_add_u64 v[126:127], s[38:39], 0, v[104:105]
	v_lshl_add_u64 v[128:129], s[48:49], 0, v[104:105]
	global_load_ushort v102, v[102:103], off
	s_nop 0
	global_load_ushort v103, v[14:15], off
	s_nop 0
	global_load_dword v14, v[106:107], off
	global_load_ushort v104, v[120:121], off
	global_load_ushort v105, v[122:123], off
	global_load_dword v15, v[124:125], off
	s_nop 0
	global_load_ushort v106, v[126:127], off
	global_load_ushort v107, v[128:129], off
	global_load_ushort v77, v[12:13], off
	global_load_ushort v79, v[18:19], off
	global_load_ushort v81, v[20:21], off
	global_load_ushort v82, v[108:109], off
	global_load_ushort v84, v[110:111], off
	global_load_dword v5, v[112:113], off
	global_load_dword v12, v[62:63], off
	global_load_dword v3, v[16:17], off
	global_load_dword v13, v[118:119], off
	s_nop 0
	global_load_dword v16, v[116:117], off
	global_load_dword v11, v[114:115], off
.LBB0_248:
	ds_read_b128 v[18:21], v91 offset:17408
	ds_read_b128 v[108:111], v92
	ds_read_b128 v[112:115], v91 offset:17472
	ds_read_b128 v[116:119], v92 offset:64
	ds_read_b128 v[120:123], v91 offset:17536
	ds_read_b128 v[124:127], v91 offset:17600
	s_waitcnt lgkmcnt(4)
	v_mfma_f32_16x16x32_bf16 v[18:21], v[18:21], v[108:111], 0
	ds_read_b128 v[108:111], v92 offset:128
	ds_read_b128 v[128:131], v92 offset:192
	v_lshl_add_u64 v[132:133], s[70:71], 0, v[58:59]
	v_add_co_u32_e32 v134, vcc, s42, v132
	s_waitcnt lgkmcnt(4)
	v_mfma_f32_16x16x32_bf16 v[18:21], v[112:115], v[116:119], v[18:21]
	ds_read_b128 v[112:115], v93
	ds_read_b128 v[116:119], v94 offset:34816
	v_lshl_add_u64 v[62:63], s[70:71], 0, v[60:61]
	v_addc_co_u32_e32 v135, vcc, 0, v133, vcc
	s_waitcnt lgkmcnt(3)
	v_mfma_f32_16x16x32_bf16 v[18:21], v[120:123], v[108:111], v[18:21]
	s_waitcnt lgkmcnt(2)
	v_mfma_f32_16x16x32_bf16 v[18:21], v[124:127], v[128:131], v[18:21]
	s_nop 7
	v_cndmask_b32_e64 v17, v18, 0, s[6:7]
	v_cndmask_b32_e64 v18, 0, v19, s[8:9]
	v_cndmask_b32_e64 v19, v20, 0, s[10:11]
	v_cndmask_b32_e64 v20, v21, 0, s[12:13]
	v_cvt_pk_bf16_f32 v18, v17, v18
	v_cvt_pk_bf16_f32 v19, v19, v20
	global_store_dwordx2 v[62:63], v[18:19], off sc1
	s_waitcnt lgkmcnt(1)
	global_store_dwordx4 v[134:135], v[112:115], off sc1
	v_add_co_u32_e32 v18, vcc, s43, v132
	ds_read_b128 v[108:111], v95
	s_nop 0
	v_addc_co_u32_e32 v19, vcc, 0, v133, vcc
	s_waitcnt lgkmcnt(1)
	global_store_dwordx4 v[18:19], v[116:119], off sc1
	ds_read_b128 v[18:21], v94 offset:53248
	v_add_co_u32_e32 v62, vcc, s44, v132
	s_nop 1
	v_addc_co_u32_e32 v63, vcc, 0, v133, vcc
	s_waitcnt lgkmcnt(0)
	global_store_dwordx4 v[62:63], v[18:21], off sc1
	s_nop 1
	v_add_co_u32_e32 v18, vcc, 0xc002000, v132
	s_nop 1
	v_addc_co_u32_e32 v19, vcc, 0, v133, vcc
	global_store_dwordx4 v[18:19], v[108:111], off sc1
	ds_read_b128 v[18:21], v96 offset:34816
	ds_read_b128 v[108:111], v96 offset:53248
	v_add_co_u32_e32 v62, vcc, 0xe002000, v132
	s_nop 1
	v_addc_co_u32_e32 v63, vcc, 0, v133, vcc
	s_waitcnt lgkmcnt(1)
	global_store_dwordx4 v[62:63], v[18:21], off sc1
	s_nop 1
	v_add_co_u32_e32 v18, vcc, 0x10002000, v132
	s_nop 1
	v_addc_co_u32_e32 v19, vcc, 0, v133, vcc
	s_waitcnt lgkmcnt(0)
	global_store_dwordx4 v[18:19], v[108:111], off sc1
	s_and_saveexec_b64 s[34:35], s[4:5]
	s_cbranch_execz .LBB0_243
	v_add_u32_e32 v17, 0, v54
	v_add_u32_e32 v17, 0x11800, v17
	ds_read_b128 v[18:21], v17
	v_lshl_add_u64 v[62:63], s[70:71], 0, v[56:57]
	s_waitcnt lgkmcnt(0)
	global_store_dwordx4 v[62:63], v[18:21], off sc1
	s_branch .LBB0_243
.Lp2_exit:
	s_waitcnt vmcnt(0)
	s_barrier
	s_cmp_gt_u32 s101, 63
	s_cbranch_scc1 .Lp2_nopub2
	s_sub_u32 s98, s45, s74
	s_lshl_b32 s98, s98, 2
	s_add_u32 s98, s98, 0x8000
	v_mov_b32_e32 v238, s98
	v_mov_b32_e32 v239, 1
	global_store_dword v238, v239, s[70:71] sc1
.Lp2_nopub2:
	v_readlane_b32 s2, v240, 0
	v_readlane_b32 s74, v240, 1
.LBB0_250:
	s_cmp_gt_i32 s73, 3
	s_cselect_b64 s[0:1], -1, 0
	s_and_b64 s[4:5], s[22:23], s[0:1]
	s_andn2_b64 vcc, exec, s[4:5]
	s_cbranch_vccnz .LBB0_314
	s_cmp_gt_i32 s72, -1
	s_mov_b64 s[4:5], -1
	s_cbranch_scc0 .LBB0_301
	s_mov_b64 s[4:5], 0
	s_branch .LBB0_301
	s_waitcnt vmcnt(0)
	v_cmp_eq_u32_e32 vcc, 0, v143
	s_waitcnt vmcnt(0)
	s_barrier
	s_and_saveexec_b64 s[4:5], vcc
	s_cbranch_execz .LBB0_300
	v_readlane_b32 s3, v242, 11
	s_waitcnt vmcnt(0) expcnt(0) lgkmcnt(0)
	s_nop 0
	v_mov_b32_e32 v1, s3
	ds_read_b32 v3, v1
	ds_read_b32 v1, v1 offset:4
	s_waitcnt lgkmcnt(1)
	v_cmp_ne_u32_e32 vcc, 0, v3
	s_cbranch_vccnz .LBB0_268
	s_add_u32 s6, s70, 0x1000
	s_addc_u32 s7, s71, 0
	s_add_u32 s8, s70, 0x1100
	s_addc_u32 s9, s71, 0
	s_add_u32 s10, s70, 0x1200
	v_readlane_b32 s3, v242, 8
	s_addc_u32 s11, s71, 0
	s_mul_i32 s3, s75, s3
	s_add_u32 s12, s70, 0x1300
	s_mul_i32 s3, s3, s74
	s_addc_u32 s13, s71, 0
	s_mov_b32 s28, 1
	v_mov_b32_e32 v17, 0
	s_branch .LBB0_256

.LBB0_346:
	s_and_b64 vcc, exec, s[0:1]
	s_cbranch_vccz .LBB0_361
	s_lshl_b32 vcc_lo, s2, 7
	s_add_u32 vcc_lo, vcc_lo, 0x8000
	v_mov_b32_e32 v237, vcc_lo
	s_mov_b32 vcc_hi, 0
.Lscan_w0:
	global_load_dword v236, v237, s[70:71] sc1
	s_waitcnt vmcnt(0)
	v_readfirstlane_b32 vcc_lo, v236
	s_cmp_lg_u32 vcc_lo, 0
	s_cbranch_scc1 .Lscan_w0done
	s_sleep 4
	s_add_u32 vcc_hi, vcc_hi, 1
	s_cmp_lt_u32 vcc_hi, 0x4000
	s_cbranch_scc1 .Lscan_w0
.Lscan_w0done:
	v_add_u32_e32 v237, 4, v237
	global_load_dword v236, v237, s[70:71] sc1
	s_lshl_b32 s0, s2, 7
	s_and_b32 s30, s0, 0x780
	s_movk_i32 s0, 0x80
	v_readfirstlane_b32 s12, v143
	v_cmp_gt_u32_e32 vcc, s0, v143
	s_and_saveexec_b64 s[0:1], vcc
	s_cbranch_execz .LBB0_349
	s_waitcnt vmcnt(0)
	v_or_b32_e32 v1, s30, v143
	v_readlane_b32 s76, v242, 12
	v_lshlrev_b32_e32 v1, 2, v1
	v_readlane_b32 s82, v242, 18
	v_readlane_b32 s83, v242, 19
	v_lshl_add_u32 v2, v143, 2, 0
	s_mov_b32 s33, s96
	v_add_u32_e32 v2, 0x1a000, v2
	v_readlane_b32 s77, v242, 13
	v_readlane_b32 s78, v242, 14
	global_load_dword v1, v1, s[82:83]
	v_readlane_b32 s79, v242, 15
	v_readlane_b32 s80, v242, 16
	v_readlane_b32 s81, v242, 17
	v_readlane_b32 s84, v242, 20
	v_readlane_b32 s85, v242, 21
	v_readlane_b32 s86, v242, 22
	v_readlane_b32 s87, v242, 23
	v_readlane_b32 s88, v242, 24
	v_readlane_b32 s89, v242, 25
	v_readlane_b32 s90, v242, 26
	v_readlane_b32 s91, v242, 27
	s_waitcnt vmcnt(0)
	ds_write_b32 v2, v1

.LBB0_350:
	v_add_u32_e32 v185, 0, v134
	s_waitcnt vmcnt(1)
	v_readfirstlane_b32 vcc_lo, v236
	s_mov_b32 vcc_hi, 0
	s_cmp_lg_u32 vcc_lo, 0
	s_cbranch_scc1 .Lscan_fok
.Lscan_fspin:
	s_sleep 2
	global_load_dword v236, v237, s[70:71] sc1
	s_waitcnt vmcnt(0)
	v_readfirstlane_b32 vcc_lo, v236
	s_cmp_lg_u32 vcc_lo, 0
	s_cbranch_scc1 .Lscan_fok
	s_add_u32 vcc_hi, vcc_hi, 1
	s_cmp_lt_u32 vcc_hi, 0x4000
	s_cbranch_scc1 .Lscan_fspin
.Lscan_fok:
	ds_write_b128 v182, v[34:37]
	ds_write_b128 v180, v[18:21] offset:34816
	ds_write_b128 v180, v[22:25] offset:53248
	ds_write_b128 v181, v[30:33]
	ds_write_b128 v179, v[66:69] offset:34816
	ds_write_b128 v179, v[78:81] offset:53248
	s_and_saveexec_b64 s[28:29], s[4:5]
	v_add_u32_e32 v2, 0x11800, v185
	ds_write_b128 v2, v[74:77]
	s_or_b64 exec, exec, s[28:29]
	s_and_saveexec_b64 s[28:29], s[0:1]
	s_cbranch_execz .LBB0_354
	s_waitcnt vmcnt(0)
	ds_write_b128 v185, v[70:73] offset:17408
.LBB0_354:
	s_or_b64 exec, exec, s[28:29]
	v_lshl_add_u64 v[146:147], s[70:71], 0, v[144:145]
	v_add_co_u32_e32 v4, vcc, 0x1ae40000, v146
	v_lshl_add_u64 v[66:67], s[70:71], 0, v[140:141]
	s_nop 0
	v_addc_co_u32_e32 v5, vcc, 0, v147, vcc
	v_add_co_u32_e32 v18, vcc, 0xc004000, v66
	s_waitcnt lgkmcnt(0)
	s_barrier
	s_nop 0
	v_addc_co_u32_e32 v19, vcc, 0, v67, vcc
	v_add_co_u32_e32 v20, vcc, 0xe004000, v66
	v_lshl_add_u64 v[2:3], v[146:147], 0, s[10:11]
	s_nop 0
	v_addc_co_u32_e32 v21, vcc, 0, v67, vcc
	v_add_co_u32_e32 v22, vcc, 0x10004000, v66
	v_add_u32_e32 v160, 0, v162
	s_nop 0
	v_addc_co_u32_e32 v23, vcc, 0, v67, vcc
	v_add_co_u32_e32 v30, vcc, 0xc006000, v66
	global_load_dwordx4 v[6:9], v[4:5], off
	s_nop 0
	global_load_dwordx4 v[2:5], v[2:3], off offset:16
	v_addc_co_u32_e32 v31, vcc, 0, v67, vcc
	global_load_dwordx4 v[34:37], v[18:19], off
	s_nop 0
	global_load_dwordx4 v[18:21], v[20:21], off
	s_nop 0
	global_load_dwordx4 v[22:25], v[22:23], off
	s_nop 0
	global_load_dwordx4 v[30:33], v[30:31], off
	ds_read2st64_b64 v[78:81], v160 offset0:34 offset1:35
	s_waitcnt vmcnt(6)
	ds_read2st64_b64 v[70:73], v160 offset0:36 offset1:37
	v_add_co_u32_e32 v118, vcc, 0xe006000, v66
	v_add_u32_e32 v176, v164, v167
	s_nop 0
	v_addc_co_u32_e32 v119, vcc, 0, v67, vcc
	v_add_u32_e32 v187, v161, v163
	s_waitcnt lgkmcnt(0)
	v_mov_b32_e32 v116, v70
	s_add_i32 s28, 0, 0x11800
	v_add_u32_e32 v70, 0x8800, v176
	v_add_co_u32_e32 v120, vcc, 0x10006000, v66
	v_add_u32_e32 v66, 0xd000, v187
	v_add_u32_e32 v189, s28, v166
	ds_read2_b64 v[82:85], v70 offset1:4
	v_add_u32_e32 v70, 0x9000, v176
	v_addc_co_u32_e32 v121, vcc, 0, v67, vcc
	ds_read2_b64 v[74:77], v66 offset1:4
	ds_read2_b64 v[66:69], v157 offset1:4
	v_add_u32_e32 v191, s28, v168
	ds_read_b128 v[86:89], v189
	ds_read_b128 v[90:93], v191
	ds_read2_b64 v[94:97], v70 offset0:32 offset1:36
	v_add_u32_e32 v70, 0x9800, v176
	ds_read2_b64 v[102:105], v70 offset0:64 offset1:68
	v_add_u32_e32 v190, s28, v169
	v_add_u32_e32 v70, 0xa000, v176
	v_add_u32_e32 v193, s28, v170
	ds_read_b128 v[110:113], v190
	ds_read_b128 v[122:125], v193
	ds_read2_b64 v[126:129], v70 offset0:96 offset1:100
	v_add_u32_e32 v70, 0xa800, v176
	v_add_u32_e32 v192, s28, v171
	ds_read2_b64 v[196:199], v70 offset0:128 offset1:132
	v_add_u32_e32 v70, 0xb000, v176
	v_add_u32_e32 v194, s28, v172
	ds_read_b128 v[200:203], v192
	ds_read_b128 v[204:207], v194
	ds_read2_b64 v[208:211], v70 offset0:160 offset1:164
	s_waitcnt lgkmcnt(10)
	v_pk_mul_f32 v[86:87], v[10:11], v[86:87]
	v_pk_mul_f32 v[88:89], v[12:13], v[88:89]
	v_add_u32_e32 v70, 0xb800, v176
	v_add_u32_e32 v184, s28, v173
	v_mfma_f32_16x16x32_bf16 v[98:101], v[82:85], v[74:77], v[86:89]
	s_waitcnt lgkmcnt(9)
	v_pk_mul_f32 v[82:83], v[38:39], v[90:91]
	v_pk_mul_f32 v[84:85], v[40:41], v[92:93]
	ds_read2_b64 v[90:93], v70 offset0:192 offset1:196
	v_add_u32_e32 v70, 0xc000, v176
	s_waitcnt lgkmcnt(9)
	v_mfma_f32_16x16x32_bf16 v[106:109], v[94:97], v[74:77], v[82:85]
	ds_read2_b64 v[94:97], v70 offset0:224 offset1:228
	v_add_u32_e32 v188, s28, v174
	ds_read_b128 v[212:215], v184
	s_waitcnt lgkmcnt(9)
	v_pk_mul_f32 v[82:83], v[42:43], v[110:111]
	v_pk_mul_f32 v[84:85], v[44:45], v[112:113]
	v_mov_b32_e32 v117, v71
	v_mov_b32_e32 v70, v80
	v_mfma_f32_16x16x32_bf16 v[110:113], v[102:105], v[74:77], v[82:85]
	v_mov_b32_e32 v71, v81
	v_cvt_pk_bf16_f32 v42, v42, v43
	v_cvt_pk_bf16_f32 v43, v44, v45
	s_waitcnt lgkmcnt(8)
	v_pk_mul_f32 v[82:83], v[46:47], v[122:123]
	v_pk_mul_f32 v[84:85], v[48:49], v[124:125]
	ds_read_b128 v[122:125], v188
	v_cvt_pk_bf16_f32 v44, v46, v47
	s_waitcnt lgkmcnt(8)
	v_mfma_f32_16x16x32_bf16 v[102:105], v[126:129], v[74:77], v[82:85]
	s_waitcnt lgkmcnt(1)
	v_pk_mul_f32 v[126:127], v[62:63], v[212:213]
	v_pk_mul_f32 v[128:129], v[64:65], v[214:215]
	s_waitcnt lgkmcnt(0)
	v_pk_mul_f32 v[122:123], v[58:59], v[122:123]
	v_pk_mul_f32 v[124:125], v[60:61], v[124:125]
	v_mfma_f32_16x16x32_bf16 v[90:93], v[90:93], v[74:77], v[126:129]
	v_cvt_pk_bf16_f32 v45, v48, v49
	v_mov_b32_e32 v114, v78
	v_mov_b32_e32 v115, v79
	v_mfma_f32_16x16x32_bf16 v[94:97], v[94:97], v[74:77], v[122:125]
	ds_read2_b64 v[126:129], v157 offset0:8 offset1:12
	v_pk_mul_f32 v[82:83], v[50:51], v[200:201]
	v_pk_mul_f32 v[84:85], v[52:53], v[202:203]
	v_add_u32_e32 v122, 0x1000, v157
	v_mfma_f32_16x16x32_bf16 v[46:49], v[74:77], v[70:73], 0
	ds_read2_b64 v[70:73], v122 offset0:40 offset1:44
	v_pk_mul_f32 v[86:87], v[54:55], v[204:205]
	v_pk_mul_f32 v[88:89], v[56:57], v[206:207]
	v_mfma_f32_16x16x32_bf16 v[82:85], v[196:199], v[74:77], v[82:85]
	v_cvt_pk_bf16_f32 v10, v10, v11
	v_cvt_pk_bf16_f32 v11, v12, v13
	v_cvt_pk_bf16_f32 v12, v38, v39
	v_mfma_f32_16x16x32_bf16 v[86:89], v[208:211], v[74:77], v[86:89]
	v_cvt_pk_bf16_f32 v13, v40, v41
	v_cvt_pk_bf16_f32 v62, v62, v63
	v_cvt_pk_bf16_f32 v63, v64, v65
	v_mfma_f32_16x16x32_bf16 v[78:81], v[74:77], v[114:117], 0
	v_cvt_pk_bf16_f32 v64, v58, v59
	v_cvt_pk_bf16_f32 v65, v60, v61
	v_cvt_pk_bf16_f32 v50, v50, v51
	s_waitcnt lgkmcnt(1)
	v_mfma_f32_16x16x32_bf16 v[74:77], v[42:45], v[126:129], 0
	v_cvt_pk_bf16_f32 v51, v52, v53
	v_cvt_pk_bf16_f32 v52, v54, v55
	v_cvt_pk_bf16_f32 v53, v56, v57
	s_waitcnt lgkmcnt(0)
	v_mfma_f32_16x16x32_bf16 v[38:41], v[42:45], v[70:73], 0
	ds_read2_b64 v[42:45], v157 offset0:24 offset1:28
	ds_read2_b64 v[70:73], v122 offset0:32 offset1:36
	v_add_u32_e32 v195, v161, v175
	v_add_u32_e32 v196, s34, v166
	v_mfma_f32_16x16x32_bf16 v[114:117], v[10:13], v[66:69], v[78:81]
	v_add_u32_e32 v183, 0x9000, v156
	v_add_u32_e32 v198, s34, v168
	v_add_u32_e32 v197, s34, v169
	s_waitcnt lgkmcnt(0)
	v_mfma_f32_16x16x32_bf16 v[10:13], v[10:13], v[70:73], v[46:49]
	s_nop 2
	ds_read2_b64 v[46:49], v157 offset0:16 offset1:20
	ds_read2_b64 v[58:61], v122 offset0:56 offset1:60
	global_load_dwordx4 v[66:69], v[118:119], off
	global_load_dwordx4 v[78:81], v[120:121], off
	ds_read2_b64 v[54:57], v122 offset0:48 offset1:52
	v_mfma_f32_16x16x32_bf16 v[42:45], v[62:65], v[42:45], v[74:77]
	v_add_u32_e32 v199, s34, v170
	v_cvt_pk_bf16_f32 v232, v98, v99
	v_cvt_pk_bf16_f32 v233, v100, v101
	s_waitcnt lgkmcnt(1)
	v_mfma_f32_16x16x32_bf16 v[38:41], v[62:65], v[58:61], v[38:41]
	v_lshl_add_u64 v[58:59], s[70:71], 0, v[138:139]
	v_lshl_add_u64 v[60:61], s[70:71], 0, v[136:137]
	global_load_dwordx4 v[74:77], v[58:59], off
	global_load_dwordx4 v[70:73], v[60:61], off
	v_add_u32_e32 v237, 4, v237
	global_load_dword v236, v237, s[70:71] sc1
	v_mfma_f32_16x16x32_bf16 v[46:49], v[50:53], v[46:49], v[114:117]
	v_cvt_pk_bf16_f32 v234, v106, v107
	v_cvt_pk_bf16_f32 v235, v108, v109
	v_add_u32_e32 v186, 0xa800, v156
	s_waitcnt lgkmcnt(0)
	v_mfma_f32_16x16x32_bf16 v[10:13], v[50:53], v[54:57], v[10:13]
	s_add_i32 s31, s31, -1
	s_nop 1
	v_pk_add_f32 v[44:45], v[44:45], v[48:49]
	v_pk_add_f32 v[42:43], v[42:43], v[46:47]
	ds_write_b128 v159, v[42:45]
	v_lshl_add_u64 v[136:137], v[136:137], 0, s[12:13]
	s_nop 0
	v_pk_add_f32 v[12:13], v[40:41], v[12:13]
	v_pk_add_f32 v[10:11], v[38:39], v[10:11]
	ds_write_b128 v159, v[10:13] offset:8448
	ds_read2st64_b64 v[10:13], v160 offset0:38 offset1:39
	ds_read2st64_b64 v[54:57], v160 offset0:40 offset1:41
	v_add_u32_e32 v38, 0xd000, v195
	ds_read2_b64 v[58:61], v38 offset1:4
	ds_read2_b64 v[50:53], v158 offset1:4
	ds_read2_b64 v[118:121], v158 offset0:8 offset1:12
	ds_read2_b64 v[46:49], v158 offset0:16 offset1:20
	ds_read2_b64 v[114:117], v158 offset0:24 offset1:28
	s_waitcnt lgkmcnt(6)
	v_mov_b32_e32 v62, v10
	v_add_u32_e32 v10, 0x3000, v157
	ds_read2_b64 v[126:129], v10 offset0:96 offset1:100
	ds_read2_b64 v[200:203], v10 offset0:104 offset1:108
	ds_read2_b64 v[122:125], v10 offset0:112 offset1:116
	ds_read2_b64 v[204:207], v10 offset0:120 offset1:124
	v_add_u32_e32 v10, 0x8800, v156
	v_mov_b32_e32 v63, v11
	s_waitcnt lgkmcnt(9)
	v_mov_b32_e32 v64, v54
	v_mov_b32_e32 v65, v55
	v_mov_b32_e32 v54, v12
	v_mov_b32_e32 v55, v13
	ds_read2_b64 v[10:13], v10 offset1:4
	ds_read_b128 v[38:41], v196
	ds_read_b128 v[42:45], v198
	ds_read2_b64 v[208:211], v183 offset0:32 offset1:36
	v_add_u32_e32 v183, 0x9800, v156
	ds_read2_b64 v[212:215], v183 offset0:64 offset1:68
	ds_read_b128 v[216:219], v197
	ds_read_b128 v[220:223], v199
	s_waitcnt lgkmcnt(5)
	v_pk_mul_f32 v[40:41], v[100:101], v[40:41]
	v_pk_mul_f32 v[38:39], v[98:99], v[38:39]
	v_mfma_f32_16x16x32_bf16 v[54:57], v[58:61], v[54:57], 0
	v_add_u32_e32 v183, 0xa000, v156
	ds_read2_b64 v[224:227], v183 offset0:96 offset1:100
	v_add_u32_e32 v183, s34, v171
	v_mfma_f32_16x16x32_bf16 v[10:13], v[10:13], v[58:61], v[38:41]
	v_add_u32_e32 v98, s34, v173
	v_add_u32_e32 v99, 0xb800, v156
	v_add_u32_e32 v100, 0xc000, v156
	s_waitcnt lgkmcnt(5)
	v_pk_mul_f32 v[40:41], v[108:109], v[44:45]
	v_pk_mul_f32 v[38:39], v[106:107], v[42:43]
	s_waitcnt lgkmcnt(2)
	v_pk_mul_f32 v[44:45], v[112:113], v[218:219]
	v_pk_mul_f32 v[42:43], v[110:111], v[216:217]
	v_cvt_pk_bf16_f32 v110, v110, v111
	v_cvt_pk_bf16_f32 v111, v112, v113
	v_cvt_pk_bf16_f32 v112, v102, v103
	v_cvt_pk_bf16_f32 v113, v104, v105
	v_mfma_f32_16x16x32_bf16 v[62:65], v[58:61], v[62:65], 0
	v_add_u32_e32 v216, 0xb000, v156
	ds_read2_b64 v[228:231], v186 offset0:128 offset1:132
	v_add_u32_e32 v186, s34, v172
	v_mfma_f32_16x16x32_bf16 v[118:121], v[110:113], v[118:121], 0
	v_lshl_add_u64 v[138:139], v[138:139], 0, s[22:23]
	v_lshl_add_u64 v[140:141], v[140:141], 0, s[24:25]
	s_cmp_eq_u32 s31, 0
	v_mfma_f32_16x16x32_bf16 v[106:109], v[110:113], v[200:203], 0
	v_cvt_pk_bf16_f32 v110, v90, v91
	v_cvt_pk_bf16_f32 v111, v92, v93
	v_cvt_pk_bf16_f32 v112, v94, v95
	v_cvt_pk_bf16_f32 v113, v96, v97
	v_mfma_f32_16x16x32_bf16 v[54:57], v[232:235], v[126:129], v[54:57]
	v_cvt_pk_bf16_f32 v126, v82, v83
	v_cvt_pk_bf16_f32 v127, v84, v85
	v_cvt_pk_bf16_f32 v128, v86, v87
	v_cvt_pk_bf16_f32 v129, v88, v89
	v_mfma_f32_16x16x32_bf16 v[50:53], v[232:235], v[50:53], v[62:65]
	v_lshl_add_u64 v[144:145], v[144:145], 0, s[26:27]
	v_mfma_f32_16x16x32_bf16 v[114:117], v[110:113], v[114:117], v[118:121]
	v_mfma_f32_16x16x32_bf16 v[46:49], v[126:129], v[46:49], v[50:53]
	v_mfma_f32_16x16x32_bf16 v[106:109], v[110:113], v[204:207], v[106:109]
	s_waitcnt lgkmcnt(2)
	s_nop 2
	v_pk_mul_f32 v[52:53], v[104:105], v[222:223]
	s_nop 1
	v_pk_add_f32 v[48:49], v[116:117], v[48:49]
	v_pk_add_f32 v[46:47], v[114:115], v[46:47]
	v_mfma_f32_16x16x32_bf16 v[54:57], v[126:129], v[122:125], v[54:57]
	v_mul_f32_e64 v50, v102, v220
	v_mul_f32_e64 v51, v103, v221
	v_mfma_f32_16x16x32_bf16 v[38:41], v[208:211], v[58:61], v[38:41]
	v_mfma_f32_16x16x32_bf16 v[42:45], v[212:215], v[58:61], v[42:45]
	ds_read_b128 v[208:211], v183
	ds_read_b128 v[212:215], v186
	ds_read2_b64 v[216:219], v216 offset0:160 offset1:164
	ds_read2_b64 v[62:65], v99 offset0:192 offset1:196
	v_add_u32_e32 v99, s34, v174
	ds_read_b128 v[110:113], v98
	ds_read_b128 v[118:121], v99
	ds_read2_b64 v[200:203], v100 offset0:224 offset1:228
	ds_write_b128 v155, v[46:49]
	v_pk_add_f32 v[48:49], v[108:109], v[56:57]
	v_pk_add_f32 v[46:47], v[106:107], v[54:55]
	ds_write_b128 v155, v[46:49] offset:8448
	s_waitcnt lgkmcnt(0)
	s_barrier
	ds_read_b128 v[104:107], v154
	ds_read_b128 v[114:117], v154 offset:16
	ds_read_b128 v[122:125], v154 offset:32
	ds_read_b128 v[126:129], v154 offset:48
	s_waitcnt lgkmcnt(14)
	v_mfma_f32_16x16x32_bf16 v[46:49], v[224:227], v[58:61], v[50:53]
	s_waitcnt lgkmcnt(3)
	s_nop 1
	v_pk_mul_f32 v[50:51], v[106:107], v[106:107]
	v_pk_mul_f32 v[52:53], v[104:105], v[104:105]
	s_nop 0
	v_pk_mov_b32 v[54:55], v[52:53], v[50:51] op_sel:[1,0]
	v_mov_b32_e32 v53, v51
	v_pk_add_f32 v[50:51], v[54:55], v[52:53]
	s_waitcnt lgkmcnt(2)
	v_pk_mul_f32 v[52:53], v[116:117], v[116:117]
	v_pk_mul_f32 v[54:55], v[114:115], v[114:115]
	v_pk_add_f32 v[50:51], v[50:51], v[50:51] op_sel:[0,1] op_sel_hi:[1,0]
	v_pk_mov_b32 v[56:57], v[54:55], v[52:53] op_sel:[1,0]
	v_mov_b32_e32 v55, v53
	v_pk_add_f32 v[52:53], v[56:57], v[54:55]
	s_waitcnt lgkmcnt(0)
	v_mul_f32_e32 v54, v126, v126
	v_mul_f32_e32 v55, v127, v127
	v_pk_add_f32 v[52:53], v[52:53], v[52:53] op_sel:[0,1] op_sel_hi:[1,0]
	v_mov_b32_e32 v51, v54
	v_mov_b32_e32 v53, v55
	v_pk_add_f32 v[50:51], v[50:51], v[52:53]
	v_mul_f32_e32 v52, v123, v123
	v_mul_f32_e32 v54, v125, v125
	v_mul_f32_e32 v56, v128, v128
	v_mul_f32_e32 v57, v129, v129
	v_pk_fma_f32 v[52:53], v[122:123], v[122:123], v[52:53] op_sel_hi:[1,1,0]
	v_pk_fma_f32 v[54:55], v[124:125], v[124:125], v[54:55] op_sel_hi:[1,1,0]
	v_mov_b32_e32 v53, v56
	v_mov_b32_e32 v55, v57
	v_pk_add_f32 v[52:53], v[52:53], v[54:55]
	v_pk_mul_f32 v[56:57], v[88:89], v[214:215]
	v_pk_add_f32 v[50:51], v[50:51], v[52:53]
	v_pk_mul_f32 v[52:53], v[84:85], v[210:211]
	v_add_f32_e32 v54, v50, v51
	v_and_b32_e32 v51, 64, v177
	v_xor_b32_e32 v50, 1, v177
	v_add_u32_e32 v102, 64, v51
	v_cmp_lt_i32_e32 vcc, v50, v102
	v_pk_mul_f32 v[84:85], v[92:93], v[112:113]
	v_add_u32_e32 v92, 0, v165
	v_cndmask_b32_e32 v50, v177, v50, vcc
	v_lshlrev_b32_e32 v100, 2, v50
	ds_bpermute_b32 v55, v100, v54
	v_pk_mul_f32 v[50:51], v[82:83], v[208:209]
	s_waitcnt lgkmcnt(0)
	v_add_f32_e32 v82, v54, v55
	v_xor_b32_e32 v54, 2, v177
	v_cmp_lt_i32_e32 vcc, v54, v102
	v_mfma_f32_16x16x32_bf16 v[50:53], v[228:231], v[58:61], v[50:53]
	s_nop 0
	v_cndmask_b32_e32 v54, v177, v54, vcc
	v_lshlrev_b32_e32 v101, 2, v54
	ds_bpermute_b32 v83, v101, v82
	v_pk_mul_f32 v[54:55], v[86:87], v[212:213]
	s_waitcnt lgkmcnt(0)
	v_add_f32_e32 v86, v82, v83
	v_xor_b32_e32 v82, 4, v177
	v_cmp_lt_i32_e32 vcc, v82, v102
	v_mfma_f32_16x16x32_bf16 v[54:57], v[216:219], v[58:61], v[54:57]
	s_nop 0
	v_cndmask_b32_e32 v82, v177, v82, vcc
	v_lshlrev_b32_e32 v102, 2, v82
	ds_bpermute_b32 v87, v102, v86
	v_pk_mul_f32 v[82:83], v[90:91], v[110:111]
	s_nop 1
	v_mfma_f32_16x16x32_bf16 v[62:65], v[62:65], v[58:61], v[82:85]
	s_waitcnt lgkmcnt(0)
	s_nop 1
	v_add_f32_e32 v82, v86, v87
	v_fmamk_f32 v82, v82, 0x3c000000, v178
	v_mul_f32_e32 v83, 0x4b800000, v82
	v_cmp_gt_f32_e32 vcc, s35, v82
	v_pk_mul_f32 v[84:85], v[96:97], v[120:121]
	s_nop 0
	v_cndmask_b32_e32 v82, v82, v83, vcc
	v_rsq_f32_e32 v86, v82
	v_pk_mul_f32 v[82:83], v[94:95], v[118:119]
	s_nop 1
	v_mfma_f32_16x16x32_bf16 v[58:61], v[200:203], v[58:61], v[82:85]
	s_nop 2
	v_mul_f32_e32 v82, 0x45800000, v86
	v_cndmask_b32_e32 v90, v86, v82, vcc
	v_pk_mul_f32 v[108:109], v[104:105], v[90:91] op_sel_hi:[1,0]
	v_add_u32_e32 v91, 0x1a000, v92
	ds_read_b128 v[82:85], v91
	v_pk_mul_f32 v[110:111], v[106:107], v[90:91] op_sel_hi:[1,0]
	ds_read_b128 v[86:89], v91 offset:16
	ds_read_b128 v[94:97], v91 offset:32
	ds_read_b128 v[104:107], v91 offset:48
	s_waitcnt lgkmcnt(3)
	v_pk_mul_f32 v[82:83], v[82:83], v[108:109]
	v_lshlrev_b32_e32 v108, 16, v26
	v_and_b32_e32 v109, 0xffff0000, v26
	v_pk_mul_f32 v[82:83], v[82:83], v[108:109]
	v_pk_mul_f32 v[84:85], v[84:85], v[110:111]
	v_cvt_pk_bf16_f32 v26, v82, v83
	v_lshlrev_b32_e32 v82, 16, v27
	v_and_b32_e32 v83, 0xffff0000, v27
	v_pk_mul_f32 v[82:83], v[84:85], v[82:83]
	v_pk_mul_f32 v[84:85], v[116:117], v[90:91] op_sel_hi:[1,0]
	v_cvt_pk_bf16_f32 v27, v82, v83
	v_pk_mul_f32 v[82:83], v[114:115], v[90:91] op_sel_hi:[1,0]
	s_waitcnt lgkmcnt(2)
	v_pk_mul_f32 v[84:85], v[88:89], v[84:85]
	v_pk_mul_f32 v[82:83], v[86:87], v[82:83]
	v_lshlrev_b32_e32 v86, 16, v28
	v_and_b32_e32 v87, 0xffff0000, v28
	v_pk_mul_f32 v[82:83], v[82:83], v[86:87]
	v_lshlrev_b32_e32 v86, 16, v14
	v_cvt_pk_bf16_f32 v28, v82, v83
	v_lshlrev_b32_e32 v82, 16, v29
	v_and_b32_e32 v83, 0xffff0000, v29
	v_pk_mul_f32 v[82:83], v[84:85], v[82:83]
	v_and_b32_e32 v87, 0xffff0000, v14
	v_cvt_pk_bf16_f32 v29, v82, v83
	v_pk_mul_f32 v[82:83], v[122:123], v[90:91] op_sel_hi:[1,0]
	v_pk_mul_f32 v[84:85], v[124:125], v[90:91] op_sel_hi:[1,0]
	s_waitcnt lgkmcnt(1)
	v_pk_mul_f32 v[82:83], v[94:95], v[82:83]
	v_pk_mul_f32 v[84:85], v[96:97], v[84:85]
	v_pk_mul_f32 v[82:83], v[82:83], v[86:87]
	v_lshlrev_b32_e32 v86, 16, v16
	v_cvt_pk_bf16_f32 v14, v82, v83
	v_lshlrev_b32_e32 v82, 16, v15
	v_and_b32_e32 v83, 0xffff0000, v15
	v_pk_mul_f32 v[82:83], v[84:85], v[82:83]
	v_and_b32_e32 v87, 0xffff0000, v16
	v_cvt_pk_bf16_f32 v15, v82, v83
	v_pk_mul_f32 v[82:83], v[126:127], v[90:91] op_sel_hi:[1,0]
	v_pk_mul_f32 v[84:85], v[128:129], v[90:91] op_sel_hi:[1,0]
	s_waitcnt lgkmcnt(0)
	v_pk_mul_f32 v[82:83], v[104:105], v[82:83]
	v_pk_mul_f32 v[84:85], v[106:107], v[84:85]
	v_pk_mul_f32 v[82:83], v[82:83], v[86:87]
	s_nop 0
	v_cvt_pk_bf16_f32 v16, v82, v83
	v_lshlrev_b32_e32 v82, 16, v17
	v_and_b32_e32 v83, 0xffff0000, v17
	v_pk_mul_f32 v[82:83], v[84:85], v[82:83]
	s_nop 0
	v_cvt_pk_bf16_f32 v17, v82, v83
	v_add_co_u32_e32 v82, vcc, s36, v146
	s_nop 1
	v_addc_co_u32_e32 v83, vcc, 0, v147, vcc
	global_store_dwordx4 v[82:83], v[26:29], off
	global_store_dwordx4 v[82:83], v[14:17], off offset:16
	s_cbranch_scc1 .LBB0_356
	s_waitcnt vmcnt(11)
	v_mov_b64_e32 v[28:29], v[8:9]
	s_waitcnt vmcnt(10)
	v_mov_b64_e32 v[16:17], v[4:5]
	v_mov_b64_e32 v[26:27], v[6:7]
	v_mov_b64_e32 v[14:15], v[2:3]
	s_branch .LBB0_350

.LBB0_379:
	s_lshl_b32 s3, s65, 8
	s_add_u32 s8, s70, s3
	s_addc_u32 s9, s71, 0
	v_mov_b32_e32 v2, 0x1000
	v_mov_b32_e32 v4, 1
	global_atomic_add v4, v2, v4, s[8:9] offset:1024 sc0
	v_cvt_f32_u32_e32 v2, v3
	v_sub_u32_e32 v5, 0, v3
	v_rcp_iflag_f32_e32 v2, v2
	s_nop 0
	v_mul_f32_e32 v2, 0x4f7ffffe, v2
	v_cvt_u32_f32_e32 v2, v2
	v_mul_lo_u32 v5, v5, v2
	v_mul_hi_u32 v5, v2, v5
	v_add_u32_e32 v2, v2, v5
	s_waitcnt vmcnt(0)
	v_mul_hi_u32 v2, v4, v2
	v_mul_lo_u32 v5, v2, v3
	v_sub_u32_e32 v5, v4, v5
	v_add_u32_e32 v6, 1, v2
	v_cmp_ge_u32_e32 vcc, v5, v3
	v_add_u32_e32 v4, 1, v4
	s_nop 0
	v_cndmask_b32_e32 v2, v2, v6, vcc
	v_sub_u32_e32 v6, v5, v3
	v_cndmask_b32_e32 v5, v5, v6, vcc
	v_add_u32_e32 v6, 1, v2
	v_cmp_ge_u32_e32 vcc, v5, v3
	s_nop 1
	v_cndmask_b32_e32 v2, v2, v6, vcc
	v_mul_lo_u32 v5, v3, v2
	v_add_u32_e32 v3, v5, v3
	v_cmp_ne_u32_e32 vcc, v4, v3
	s_and_saveexec_b64 s[10:11], vcc
	s_xor_b64 s[10:11], exec, s[10:11]
	s_cbranch_execz .LBB0_393
	s_waitcnt lgkmcnt(0)
	v_mov_b32_e32 v1, 0x3500
	global_load_dword v1, v1, s[70:71] sc1
	s_add_u32 s22, s70, 0x3500
	s_addc_u32 s23, s71, 0
	v_mov_b32_e32 v2, 2
	s_waitcnt vmcnt(0)
	v_cmp_eq_u32_e32 vcc, v1, v2
	s_and_saveexec_b64 s[12:13], vcc
	s_cbranch_execz .LBB0_392
	s_mov_b32 s3, 1
	s_mov_b64 s[24:25], 0
	v_mov_b32_e32 v1, 0
	s_branch .LBB0_383

.LBB0_482:
	s_lshl_b32 s3, s65, 8
	s_add_u32 s8, s70, s3
	s_addc_u32 s9, s71, 0
	v_mov_b32_e32 v2, 0x1000
	v_mov_b32_e32 v4, 1
	global_atomic_add v4, v2, v4, s[8:9] offset:1024 sc0
	v_cvt_f32_u32_e32 v2, v3
	v_sub_u32_e32 v5, 0, v3
	v_rcp_iflag_f32_e32 v2, v2
	s_nop 0
	v_mul_f32_e32 v2, 0x4f7ffffe, v2
	v_cvt_u32_f32_e32 v2, v2
	v_mul_lo_u32 v5, v5, v2
	v_mul_hi_u32 v5, v2, v5
	v_add_u32_e32 v2, v2, v5
	s_waitcnt vmcnt(0)
	v_mul_hi_u32 v2, v4, v2
	v_mul_lo_u32 v5, v2, v3
	v_sub_u32_e32 v5, v4, v5
	v_add_u32_e32 v6, 1, v2
	v_cmp_ge_u32_e32 vcc, v5, v3
	v_add_u32_e32 v4, 1, v4
	s_nop 0
	v_cndmask_b32_e32 v2, v2, v6, vcc
	v_sub_u32_e32 v6, v5, v3
	v_cndmask_b32_e32 v5, v5, v6, vcc
	v_add_u32_e32 v6, 1, v2
	v_cmp_ge_u32_e32 vcc, v5, v3
	s_nop 1
	v_cndmask_b32_e32 v2, v2, v6, vcc
	v_mul_lo_u32 v5, v3, v2
	v_add_u32_e32 v3, v5, v3
	v_cmp_ne_u32_e32 vcc, v4, v3
	s_and_saveexec_b64 s[10:11], vcc
	s_xor_b64 s[10:11], exec, s[10:11]
	s_cbranch_execz .LBB0_496
	s_waitcnt lgkmcnt(0)
	v_mov_b32_e32 v1, 0x3500
	global_load_dword v1, v1, s[70:71] sc1
	s_add_u32 s20, s70, 0x3500
	s_addc_u32 s21, s71, 0
	v_mov_b32_e32 v2, 3
	s_waitcnt vmcnt(0)
	v_cmp_eq_u32_e32 vcc, v1, v2
	s_and_saveexec_b64 s[12:13], vcc
	s_cbranch_execz .LBB0_495
	s_mov_b32 s3, 1
	s_mov_b64 s[22:23], 0
	v_mov_b32_e32 v1, 0
	s_branch .LBB0_486

.LBB0_640:
	s_lshl_b32 s3, s65, 8
	s_add_u32 s6, s70, s3
	s_addc_u32 s7, s71, 0
	v_mov_b32_e32 v2, 0x1000
	v_mov_b32_e32 v4, 1
	global_atomic_add v4, v2, v4, s[6:7] offset:1024 sc0
	v_cvt_f32_u32_e32 v2, v3
	v_sub_u32_e32 v5, 0, v3
	v_rcp_iflag_f32_e32 v2, v2
	s_nop 0
	v_mul_f32_e32 v2, 0x4f7ffffe, v2
	v_cvt_u32_f32_e32 v2, v2
	v_mul_lo_u32 v5, v5, v2
	v_mul_hi_u32 v5, v2, v5
	v_add_u32_e32 v2, v2, v5
	s_waitcnt vmcnt(0)
	v_mul_hi_u32 v2, v4, v2
	v_mul_lo_u32 v5, v2, v3
	v_sub_u32_e32 v5, v4, v5
	v_add_u32_e32 v6, 1, v2
	v_cmp_ge_u32_e32 vcc, v5, v3
	v_add_u32_e32 v4, 1, v4
	s_nop 0
	v_cndmask_b32_e32 v2, v2, v6, vcc
	v_sub_u32_e32 v6, v5, v3
	v_cndmask_b32_e32 v5, v5, v6, vcc
	v_add_u32_e32 v6, 1, v2
	v_cmp_ge_u32_e32 vcc, v5, v3
	s_nop 1
	v_cndmask_b32_e32 v2, v2, v6, vcc
	v_mul_lo_u32 v5, v3, v2
	v_add_u32_e32 v3, v5, v3
	v_cmp_ne_u32_e32 vcc, v4, v3
	s_and_saveexec_b64 s[8:9], vcc
	s_xor_b64 s[8:9], exec, s[8:9]
	s_cbranch_execz .LBB0_654
	s_waitcnt lgkmcnt(0)
	v_mov_b32_e32 v1, 0x3500
	global_load_dword v1, v1, s[70:71] sc1
	s_add_u32 s12, s70, 0x3500
	s_addc_u32 s13, s71, 0
	v_mov_b32_e32 v2, 5
	s_waitcnt vmcnt(0)
	v_cmp_eq_u32_e32 vcc, v1, v2
	s_and_saveexec_b64 s[10:11], vcc
	s_cbranch_execz .LBB0_653
	s_mov_b32 s3, 1
	s_mov_b64 s[20:21], 0
	v_mov_b32_e32 v1, 0
	s_branch .LBB0_644

.LBB0_743:
	s_lshl_b32 s3, s65, 8
	s_add_u32 s6, s70, s3
	s_addc_u32 s7, s71, 0
	v_mov_b32_e32 v2, 0x1000
	v_mov_b32_e32 v4, 1
	global_atomic_add v4, v2, v4, s[6:7] offset:1024 sc0
	v_cvt_f32_u32_e32 v2, v3
	v_sub_u32_e32 v5, 0, v3
	v_rcp_iflag_f32_e32 v2, v2
	s_nop 0
	v_mul_f32_e32 v2, 0x4f7ffffe, v2
	v_cvt_u32_f32_e32 v2, v2
	v_mul_lo_u32 v5, v5, v2
	v_mul_hi_u32 v5, v2, v5
	v_add_u32_e32 v2, v2, v5
	s_waitcnt vmcnt(0)
	v_mul_hi_u32 v2, v4, v2
	v_mul_lo_u32 v5, v2, v3
	v_sub_u32_e32 v5, v4, v5
	v_add_u32_e32 v6, 1, v2
	v_cmp_ge_u32_e32 vcc, v5, v3
	v_add_u32_e32 v4, 1, v4
	s_nop 0
	v_cndmask_b32_e32 v2, v2, v6, vcc
	v_sub_u32_e32 v6, v5, v3
	v_cndmask_b32_e32 v5, v5, v6, vcc
	v_add_u32_e32 v6, 1, v2
	v_cmp_ge_u32_e32 vcc, v5, v3
	s_nop 1
	v_cndmask_b32_e32 v2, v2, v6, vcc
	v_mul_lo_u32 v5, v3, v2
	v_add_u32_e32 v3, v5, v3
	v_cmp_ne_u32_e32 vcc, v4, v3
	s_and_saveexec_b64 s[8:9], vcc
	s_xor_b64 s[8:9], exec, s[8:9]
	s_cbranch_execz .LBB0_757
	s_waitcnt lgkmcnt(0)
	v_mov_b32_e32 v1, 0x3500
	global_load_dword v1, v1, s[70:71] sc1
	s_add_u32 s12, s70, 0x3500
	s_addc_u32 s13, s71, 0
	v_mov_b32_e32 v2, 6
	s_waitcnt vmcnt(0)
	v_cmp_eq_u32_e32 vcc, v1, v2
	s_and_saveexec_b64 s[10:11], vcc
	s_cbranch_execz .LBB0_756
	s_mov_b32 s3, 1
	s_mov_b64 s[18:19], 0
	v_mov_b32_e32 v1, 0
	s_branch .LBB0_747

.LBB0_1064:
	s_lshl_b32 s3, s65, 8
	s_add_u32 s6, s70, s3
	s_addc_u32 s7, s71, 0
	v_mov_b32_e32 v2, 0x1000
	v_mov_b32_e32 v4, 1
	global_atomic_add v4, v2, v4, s[6:7] offset:1024 sc0
	v_cvt_f32_u32_e32 v2, v3
	v_sub_u32_e32 v5, 0, v3
	v_rcp_iflag_f32_e32 v2, v2
	s_nop 0
	v_mul_f32_e32 v2, 0x4f7ffffe, v2
	v_cvt_u32_f32_e32 v2, v2
	v_mul_lo_u32 v5, v5, v2
	v_mul_hi_u32 v5, v2, v5
	v_add_u32_e32 v2, v2, v5
	s_waitcnt vmcnt(0)
	v_mul_hi_u32 v2, v4, v2
	v_mul_lo_u32 v5, v2, v3
	v_sub_u32_e32 v5, v4, v5
	v_add_u32_e32 v6, 1, v2
	v_cmp_ge_u32_e32 vcc, v5, v3
	v_add_u32_e32 v4, 1, v4
	s_nop 0
	v_cndmask_b32_e32 v2, v2, v6, vcc
	v_sub_u32_e32 v6, v5, v3
	v_cndmask_b32_e32 v5, v5, v6, vcc
	v_add_u32_e32 v6, 1, v2
	v_cmp_ge_u32_e32 vcc, v5, v3
	s_nop 1
	v_cndmask_b32_e32 v2, v2, v6, vcc
	v_mul_lo_u32 v5, v3, v2
	v_add_u32_e32 v3, v5, v3
	v_cmp_ne_u32_e32 vcc, v4, v3
	s_and_saveexec_b64 s[8:9], vcc
	s_xor_b64 s[8:9], exec, s[8:9]
	s_cbranch_execz .LBB0_1078
	s_waitcnt lgkmcnt(0)
	v_mov_b32_e32 v1, 0x3500
	global_load_dword v1, v1, s[70:71] sc1
	s_add_u32 s12, s70, 0x3500
	s_addc_u32 s13, s71, 0
	v_mov_b32_e32 v2, 8
	s_waitcnt vmcnt(0)
	v_cmp_eq_u32_e32 vcc, v1, v2
	s_and_saveexec_b64 s[10:11], vcc
	s_cbranch_execz .LBB0_1077
	s_mov_b32 s3, 1
	s_mov_b64 s[14:15], 0
	v_mov_b32_e32 v1, 0
	s_branch .LBB0_1068

.LBB0_1556:
	s_lshl_b32 s4, s65, 8
	s_add_u32 s4, s70, s4
	s_addc_u32 s5, s71, 0
	v_mov_b32_e32 v2, 0x1000
	v_mov_b32_e32 v4, 1
	global_atomic_add v4, v2, v4, s[4:5] offset:1024 sc0
	v_cvt_f32_u32_e32 v2, v3
	v_sub_u32_e32 v5, 0, v3
	v_rcp_iflag_f32_e32 v2, v2
	s_nop 0
	v_mul_f32_e32 v2, 0x4f7ffffe, v2
	v_cvt_u32_f32_e32 v2, v2
	v_mul_lo_u32 v5, v5, v2
	v_mul_hi_u32 v5, v2, v5
	v_add_u32_e32 v2, v2, v5
	s_waitcnt vmcnt(0)
	v_mul_hi_u32 v2, v4, v2
	v_mul_lo_u32 v5, v2, v3
	v_sub_u32_e32 v5, v4, v5
	v_add_u32_e32 v6, 1, v2
	v_cmp_ge_u32_e32 vcc, v5, v3
	v_add_u32_e32 v4, 1, v4
	s_nop 0
	v_cndmask_b32_e32 v2, v2, v6, vcc
	v_sub_u32_e32 v6, v5, v3
	v_cndmask_b32_e32 v5, v5, v6, vcc
	v_add_u32_e32 v6, 1, v2
	v_cmp_ge_u32_e32 vcc, v5, v3
	s_nop 1
	v_cndmask_b32_e32 v2, v2, v6, vcc
	v_mul_lo_u32 v5, v3, v2
	v_add_u32_e32 v3, v5, v3
	v_cmp_ne_u32_e32 vcc, v4, v3
	s_and_saveexec_b64 s[6:7], vcc
	s_xor_b64 s[6:7], exec, s[6:7]
	s_cbranch_execz .LBB0_1570
	s_waitcnt lgkmcnt(0)
	v_mov_b32_e32 v1, 0x3500
	global_load_dword v1, v1, s[70:71] sc1
	s_add_u32 s10, s70, 0x3500
	s_addc_u32 s11, s71, 0
	v_mov_b32_e32 v2, 13
	s_waitcnt vmcnt(0)
	v_cmp_eq_u32_e32 vcc, v1, v2
	s_and_saveexec_b64 s[8:9], vcc
	s_cbranch_execz .LBB0_1569
	s_mov_b32 s22, 1
	s_mov_b64 s[12:13], 0
	v_mov_b32_e32 v1, 0
	s_branch .LBB0_1560

	.amdhsa_kernel _Z6mk_fwd4Args
		.amdhsa_group_segment_fixed_size 0
		.amdhsa_private_segment_fixed_size 0
		.amdhsa_kernarg_size 440
		.amdhsa_user_sgpr_count 2
		.amdhsa_user_sgpr_dispatch_ptr 0
		.amdhsa_user_sgpr_queue_ptr 0
		.amdhsa_user_sgpr_kernarg_segment_ptr 1
		.amdhsa_user_sgpr_dispatch_id 0
		.amdhsa_user_sgpr_kernarg_preload_length 0
		.amdhsa_user_sgpr_kernarg_preload_offset 0
		.amdhsa_user_sgpr_private_segment_size 0
		.amdhsa_uses_dynamic_stack 0
		.amdhsa_enable_private_segment 0
		.amdhsa_system_sgpr_workgroup_id_x 1
		.amdhsa_system_sgpr_workgroup_id_y 0
		.amdhsa_system_sgpr_workgroup_id_z 0
		.amdhsa_system_sgpr_workgroup_info 0
		.amdhsa_system_vgpr_workitem_id 2
		.amdhsa_next_free_vgpr 243
		.amdhsa_next_free_sgpr 102
		.amdhsa_accum_offset 244
		.amdhsa_reserve_vcc 1
		.amdhsa_float_round_mode_32 0
		.amdhsa_float_round_mode_16_64 0
		.amdhsa_float_denorm_mode_32 3
		.amdhsa_float_denorm_mode_16_64 3
		.amdhsa_dx10_clamp 1
		.amdhsa_ieee_mode 1
		.amdhsa_fp16_overflow 0
		.amdhsa_tg_split 0
		.amdhsa_exception_fp_ieee_invalid_op 0
		.amdhsa_exception_fp_denorm_src 0
		.amdhsa_exception_fp_ieee_div_zero 0
		.amdhsa_exception_fp_ieee_overflow 0
		.amdhsa_exception_fp_ieee_underflow 0
		.amdhsa_exception_fp_ieee_inexact 0
		.amdhsa_exception_int_div_zero 0
	.end_amdhsa_kernel

amdhsa.kernels:
  - .agpr_count:     0
    .args:
      - .offset:         0
        .size:           184
        .value_kind:     by_value
      - .offset:         184
        .size:           4
        .value_kind:     hidden_block_count_x
      - .offset:         188
        .size:           4
        .value_kind:     hidden_block_count_y
      - .offset:         192
        .size:           4
        .value_kind:     hidden_block_count_z
      - .offset:         196
        .size:           2
        .value_kind:     hidden_group_size_x
      - .offset:         198
        .size:           2
        .value_kind:     hidden_group_size_y
      - .offset:         200
        .size:           2
        .value_kind:     hidden_group_size_z
      - .offset:         202
        .size:           2
        .value_kind:     hidden_remainder_x
      - .offset:         204
        .size:           2
        .value_kind:     hidden_remainder_y
      - .offset:         206
        .size:           2
        .value_kind:     hidden_remainder_z
      - .offset:         224
        .size:           8
        .value_kind:     hidden_global_offset_x
      - .offset:         232
        .size:           8
        .value_kind:     hidden_global_offset_y
      - .offset:         240
        .size:           8
        .value_kind:     hidden_global_offset_z
      - .offset:         248
        .size:           2
        .value_kind:     hidden_grid_dims
      - .offset:         272
        .size:           8
        .value_kind:     hidden_multigrid_sync_arg
      - .offset:         304
        .size:           4
        .value_kind:     hidden_dynamic_lds_size
    .group_segment_fixed_size: 0
    .kernarg_segment_align: 8
    .kernarg_segment_size: 440
    .language:       OpenCL C
    .language_version:
      - 2
      - 0
    .max_flat_workgroup_size: 512
    .name:           _Z6mk_fwd4Args
    .private_segment_fixed_size: 0
    .sgpr_count:     108
    .sgpr_spill_count: 59
    .symbol:         _Z6mk_fwd4Args.kd
    .uniform_work_group_size: 1
    .uses_dynamic_stack: false
    .vgpr_count:     243
    .vgpr_spill_count: 0
    .wavefront_size: 64
